# 4/4 LDS-DMA balance in int8 GEMM1 K-loop (vmcnt 8/6) + s_setprio removed from all five GEMM K-loops
# speedup vs baseline: 1.0094x; 1.0094x over previous
.LBB0_230:
	s_add_u32 s28, s0, 0xfff00080
	s_addc_u32 s29, s1, -1
	s_add_i32 s51, 0, 0x10000
	s_cmp_eq_u32 s50, 60
	s_cselect_b32 s31, s34, s29
	s_cselect_b32 s30, s35, s28
	v_add_u32_e32 v0, s51, v179
	s_cselect_b32 s29, s27, s43
	s_cselect_b32 s28, s40, s41
	s_add_i32 s77, 0, 0x14000
	ds_read_b128 v[130:133], v0
	ds_read_b128 v[134:137], v0 offset:1024
	ds_read_b128 v[138:141], v0 offset:2048
	ds_read_b128 v[142:145], v0 offset:3072
	v_add_u32_e32 v0, s77, v179
	ds_read_b128 v[146:149], v0
	ds_read_b128 v[150:153], v0 offset:1024
	ds_read_b128 v[154:157], v0 offset:2048
	ds_read_b128 v[158:161], v0 offset:3072
	v_lshl_add_u64 v[194:195], s[0:1], 0, v[170:171]
	s_add_i32 m0, s14, 0xc000
	ds_read_b128 v[174:177], v192
	ds_read_b128 v[180:183], v192 offset:1024
	ds_read_b128 v[184:187], v192 offset:2048
	ds_read_b128 v[188:191], v192 offset:3072
	ds_read_b128 v[200:203], v192 offset:4096
	ds_read_b128 v[204:207], v192 offset:5120
	ds_read_b128 v[208:211], v192 offset:6144
	ds_read_b128 v[212:215], v192 offset:7168
	global_load_lds_dwordx4 v[194:195], off
	v_lshl_add_u64 v[194:195], s[0:1], 0, v[172:173]
	s_add_i32 m0, s14, 0xe000
	s_nop 0
	global_load_lds_dwordx4 v[194:195], off
	s_waitcnt vmcnt(8)
	s_waitcnt lgkmcnt(0)
	s_barrier
	s_waitcnt lgkmcnt(0)
	v_mfma_f32_16x16x32_bf16 v[126:129], v[130:133], v[174:177], v[126:129]
	v_mfma_f32_16x16x32_bf16 v[122:125], v[138:141], v[174:177], v[122:125]
	v_mfma_f32_16x16x32_bf16 v[110:113], v[130:133], v[184:187], v[110:113]
	v_mfma_f32_16x16x32_bf16 v[106:109], v[138:141], v[184:187], v[106:109]
	v_mfma_f32_16x16x32_bf16 v[94:97], v[130:133], v[200:203], v[94:97]
	v_mfma_f32_16x16x32_bf16 v[90:93], v[138:141], v[200:203], v[90:93]
	v_mfma_f32_16x16x32_bf16 v[78:81], v[130:133], v[208:211], v[78:81]
	v_mfma_f32_16x16x32_bf16 v[74:77], v[138:141], v[208:211], v[74:77]
	v_mfma_f32_16x16x32_bf16 v[126:129], v[134:137], v[180:183], v[126:129]
	v_mfma_f32_16x16x32_bf16 v[122:125], v[142:145], v[180:183], v[122:125]
	v_mfma_f32_16x16x32_bf16 v[110:113], v[134:137], v[188:191], v[110:113]
	v_mfma_f32_16x16x32_bf16 v[106:109], v[142:145], v[188:191], v[106:109]
	v_mfma_f32_16x16x32_bf16 v[94:97], v[134:137], v[204:207], v[94:97]
	v_mfma_f32_16x16x32_bf16 v[90:93], v[142:145], v[204:207], v[90:93]
	v_mfma_f32_16x16x32_bf16 v[78:81], v[134:137], v[212:215], v[78:81]
	v_mfma_f32_16x16x32_bf16 v[74:77], v[142:145], v[212:215], v[74:77]
	v_mfma_f32_16x16x32_bf16 v[118:121], v[146:149], v[174:177], v[118:121]
	v_mfma_f32_16x16x32_bf16 v[114:117], v[154:157], v[174:177], v[114:117]
	v_mfma_f32_16x16x32_bf16 v[102:105], v[146:149], v[184:187], v[102:105]
	v_mfma_f32_16x16x32_bf16 v[98:101], v[154:157], v[184:187], v[98:101]
	v_mfma_f32_16x16x32_bf16 v[86:89], v[146:149], v[200:203], v[86:89]
	v_mfma_f32_16x16x32_bf16 v[82:85], v[154:157], v[200:203], v[82:85]
	v_mfma_f32_16x16x32_bf16 v[70:73], v[146:149], v[208:211], v[70:73]
	v_mfma_f32_16x16x32_bf16 v[66:69], v[154:157], v[208:211], v[66:69]
	v_mfma_f32_16x16x32_bf16 v[118:121], v[150:153], v[180:183], v[118:121]
	v_mfma_f32_16x16x32_bf16 v[114:117], v[158:161], v[180:183], v[114:117]
	v_mfma_f32_16x16x32_bf16 v[102:105], v[150:153], v[188:191], v[102:105]
	v_mfma_f32_16x16x32_bf16 v[98:101], v[158:161], v[188:191], v[98:101]
	v_mfma_f32_16x16x32_bf16 v[86:89], v[150:153], v[204:207], v[86:89]
	v_mfma_f32_16x16x32_bf16 v[82:85], v[158:161], v[204:207], v[82:85]
	v_mfma_f32_16x16x32_bf16 v[70:73], v[150:153], v[212:215], v[70:73]
	v_mfma_f32_16x16x32_bf16 v[66:69], v[158:161], v[212:215], v[66:69]
	s_barrier
	s_add_i32 s51, s51, s9
	v_lshl_add_u64 v[194:195], s[28:29], 0, v[166:167]
	s_mov_b32 m0, s51
	ds_read_b128 v[174:177], v192 offset:16384
	ds_read_b128 v[180:183], v192 offset:17408
	ds_read_b128 v[184:187], v192 offset:18432
	ds_read_b128 v[188:191], v192 offset:19456
	ds_read_b128 v[200:203], v192 offset:20480
	ds_read_b128 v[204:207], v192 offset:21504
	ds_read_b128 v[208:211], v192 offset:22528
	ds_read_b128 v[212:215], v192 offset:23552
	global_load_lds_dwordx4 v[194:195], off
	s_add_i32 m0, s51, 0x2000
	s_add_u32 s80, s28, 0x100000
	v_lshl_add_u64 v[216:217], s[28:29], 0, v[162:163]
	s_addc_u32 s81, s29, 0
	s_add_i32 s51, s77, s9
	global_load_lds_dwordx4 v[216:217], off
	v_lshl_add_u64 v[218:219], s[80:81], 0, v[166:167]
	s_mov_b32 m0, s51
	v_lshl_add_u64 v[220:221], s[30:31], 0, v[164:165]
	global_load_lds_dwordx4 v[218:219], off
	v_lshl_add_u64 v[218:219], s[80:81], 0, v[162:163]
	s_add_i32 m0, s51, 0x2000
	s_nop 0
	global_load_lds_dwordx4 v[218:219], off
	v_lshl_add_u64 v[218:219], s[30:31], 0, v[168:169]
	s_mov_b32 m0, s14
	s_nop 0
	global_load_lds_dwordx4 v[218:219], off
	s_mov_b32 m0, s15
	s_nop 0
	global_load_lds_dwordx4 v[220:221], off
	s_waitcnt vmcnt(8)
	s_waitcnt lgkmcnt(0)
	s_barrier
	s_waitcnt lgkmcnt(0)
	v_mfma_f32_16x16x32_bf16 v[62:65], v[130:133], v[174:177], v[62:65]
	v_mfma_f32_16x16x32_bf16 v[58:61], v[138:141], v[174:177], v[58:61]
	v_mfma_f32_16x16x32_bf16 v[46:49], v[130:133], v[184:187], v[46:49]
	v_mfma_f32_16x16x32_bf16 v[42:45], v[138:141], v[184:187], v[42:45]
	v_mfma_f32_16x16x32_bf16 v[30:33], v[130:133], v[200:203], v[30:33]
	v_mfma_f32_16x16x32_bf16 v[26:29], v[138:141], v[200:203], v[26:29]
	v_mfma_f32_16x16x32_bf16 v[14:17], v[130:133], v[208:211], v[14:17]
	v_mfma_f32_16x16x32_bf16 v[10:13], v[138:141], v[208:211], v[10:13]
	v_mfma_f32_16x16x32_bf16 v[62:65], v[134:137], v[180:183], v[62:65]
	v_mfma_f32_16x16x32_bf16 v[58:61], v[142:145], v[180:183], v[58:61]
	v_mfma_f32_16x16x32_bf16 v[46:49], v[134:137], v[188:191], v[46:49]
	v_mfma_f32_16x16x32_bf16 v[42:45], v[142:145], v[188:191], v[42:45]
	v_mfma_f32_16x16x32_bf16 v[30:33], v[134:137], v[204:207], v[30:33]
	v_mfma_f32_16x16x32_bf16 v[26:29], v[142:145], v[204:207], v[26:29]
	v_mfma_f32_16x16x32_bf16 v[14:17], v[134:137], v[212:215], v[14:17]
	v_mfma_f32_16x16x32_bf16 v[10:13], v[142:145], v[212:215], v[10:13]
	v_mfma_f32_16x16x32_bf16 v[54:57], v[146:149], v[174:177], v[54:57]
	v_mfma_f32_16x16x32_bf16 v[50:53], v[154:157], v[174:177], v[50:53]
	v_mfma_f32_16x16x32_bf16 v[38:41], v[146:149], v[184:187], v[38:41]
	v_mfma_f32_16x16x32_bf16 v[34:37], v[154:157], v[184:187], v[34:37]
	v_mfma_f32_16x16x32_bf16 v[22:25], v[146:149], v[200:203], v[22:25]
	v_mfma_f32_16x16x32_bf16 v[18:21], v[154:157], v[200:203], v[18:21]
	v_mfma_f32_16x16x32_bf16 v[6:9], v[146:149], v[208:211], v[6:9]
	v_mfma_f32_16x16x32_bf16 v[2:5], v[154:157], v[208:211], v[2:5]
	v_mfma_f32_16x16x32_bf16 v[54:57], v[150:153], v[180:183], v[54:57]
	v_mfma_f32_16x16x32_bf16 v[50:53], v[158:161], v[180:183], v[50:53]
	v_mfma_f32_16x16x32_bf16 v[38:41], v[150:153], v[188:191], v[38:41]
	v_mfma_f32_16x16x32_bf16 v[34:37], v[158:161], v[188:191], v[34:37]
	v_mfma_f32_16x16x32_bf16 v[22:25], v[150:153], v[204:207], v[22:25]
	v_mfma_f32_16x16x32_bf16 v[18:21], v[158:161], v[204:207], v[18:21]
	v_mfma_f32_16x16x32_bf16 v[6:9], v[150:153], v[212:215], v[6:9]
	v_mfma_f32_16x16x32_bf16 v[2:5], v[158:161], v[212:215], v[2:5]
	s_barrier
	s_add_i32 s51, 0, 0x18000
	v_add_u32_e32 v0, s51, v179
	s_add_i32 s77, 0, 0x1c000
	ds_read_b128 v[130:133], v0
	ds_read_b128 v[134:137], v0 offset:1024
	ds_read_b128 v[138:141], v0 offset:2048
	ds_read_b128 v[142:145], v0 offset:3072
	v_add_u32_e32 v0, s77, v179
	ds_read_b128 v[146:149], v0
	ds_read_b128 v[150:153], v0 offset:1024
	ds_read_b128 v[154:157], v0 offset:2048
	ds_read_b128 v[158:161], v0 offset:3072
	s_add_u32 s30, s30, 0x100000
	s_addc_u32 s31, s31, 0
	s_mov_b32 m0, s52
	v_lshl_add_u64 v[222:223], s[30:31], 0, v[168:169]
	ds_read_b128 v[174:177], v192 offset:32768
	ds_read_b128 v[180:183], v192 offset:33792
	ds_read_b128 v[184:187], v192 offset:34816
	ds_read_b128 v[188:191], v192 offset:35840
	ds_read_b128 v[200:203], v192 offset:36864
	ds_read_b128 v[204:207], v192 offset:37888
	ds_read_b128 v[208:211], v192 offset:38912
	ds_read_b128 v[212:215], v192 offset:39936
	global_load_lds_dwordx4 v[222:223], off
	v_lshl_add_u64 v[222:223], s[30:31], 0, v[164:165]
	s_mov_b32 m0, s53
	s_nop 0
	global_load_lds_dwordx4 v[222:223], off
	s_waitcnt vmcnt(8)
	s_waitcnt lgkmcnt(0)
	s_barrier
	s_waitcnt lgkmcnt(0)
	v_mfma_f32_16x16x32_bf16 v[126:129], v[130:133], v[174:177], v[126:129]
	v_mfma_f32_16x16x32_bf16 v[122:125], v[138:141], v[174:177], v[122:125]
	v_mfma_f32_16x16x32_bf16 v[110:113], v[130:133], v[184:187], v[110:113]
	v_mfma_f32_16x16x32_bf16 v[106:109], v[138:141], v[184:187], v[106:109]
	v_mfma_f32_16x16x32_bf16 v[94:97], v[130:133], v[200:203], v[94:97]
	v_mfma_f32_16x16x32_bf16 v[90:93], v[138:141], v[200:203], v[90:93]
	v_mfma_f32_16x16x32_bf16 v[78:81], v[130:133], v[208:211], v[78:81]
	v_mfma_f32_16x16x32_bf16 v[74:77], v[138:141], v[208:211], v[74:77]
	v_mfma_f32_16x16x32_bf16 v[126:129], v[134:137], v[180:183], v[126:129]
	v_mfma_f32_16x16x32_bf16 v[122:125], v[142:145], v[180:183], v[122:125]
	v_mfma_f32_16x16x32_bf16 v[110:113], v[134:137], v[188:191], v[110:113]
	v_mfma_f32_16x16x32_bf16 v[106:109], v[142:145], v[188:191], v[106:109]
	v_mfma_f32_16x16x32_bf16 v[94:97], v[134:137], v[204:207], v[94:97]
	v_mfma_f32_16x16x32_bf16 v[90:93], v[142:145], v[204:207], v[90:93]
	v_mfma_f32_16x16x32_bf16 v[78:81], v[134:137], v[212:215], v[78:81]
	v_mfma_f32_16x16x32_bf16 v[74:77], v[142:145], v[212:215], v[74:77]
	v_mfma_f32_16x16x32_bf16 v[118:121], v[146:149], v[174:177], v[118:121]
	v_mfma_f32_16x16x32_bf16 v[114:117], v[154:157], v[174:177], v[114:117]
	v_mfma_f32_16x16x32_bf16 v[102:105], v[146:149], v[184:187], v[102:105]
	v_mfma_f32_16x16x32_bf16 v[98:101], v[154:157], v[184:187], v[98:101]
	v_mfma_f32_16x16x32_bf16 v[86:89], v[146:149], v[200:203], v[86:89]
	v_mfma_f32_16x16x32_bf16 v[82:85], v[154:157], v[200:203], v[82:85]
	v_mfma_f32_16x16x32_bf16 v[70:73], v[146:149], v[208:211], v[70:73]
	v_mfma_f32_16x16x32_bf16 v[66:69], v[154:157], v[208:211], v[66:69]
	v_mfma_f32_16x16x32_bf16 v[118:121], v[150:153], v[180:183], v[118:121]
	v_mfma_f32_16x16x32_bf16 v[114:117], v[158:161], v[180:183], v[114:117]
	v_mfma_f32_16x16x32_bf16 v[102:105], v[150:153], v[188:191], v[102:105]
	v_mfma_f32_16x16x32_bf16 v[98:101], v[158:161], v[188:191], v[98:101]
	v_mfma_f32_16x16x32_bf16 v[86:89], v[150:153], v[204:207], v[86:89]
	v_mfma_f32_16x16x32_bf16 v[82:85], v[158:161], v[204:207], v[82:85]
	v_mfma_f32_16x16x32_bf16 v[70:73], v[150:153], v[212:215], v[70:73]
	v_mfma_f32_16x16x32_bf16 v[66:69], v[158:161], v[212:215], v[66:69]
	s_barrier
	s_add_i32 s30, s51, s9
	v_lshl_add_u64 v[194:195], v[194:195], 0, s[12:13]
	s_mov_b32 m0, s30
	ds_read_b128 v[174:177], v192 offset:49152
	ds_read_b128 v[180:183], v192 offset:50176
	ds_read_b128 v[184:187], v192 offset:51200
	ds_read_b128 v[188:191], v192 offset:52224
	ds_read_b128 v[200:203], v192 offset:53248
	ds_read_b128 v[204:207], v192 offset:54272
	ds_read_b128 v[208:211], v192 offset:55296
	ds_read_b128 v[212:215], v192 offset:56320
	global_load_lds_dwordx4 v[194:195], off
	s_add_i32 m0, s30, 0x2000
	s_add_u32 s28, s28, 0x100080
	v_lshl_add_u64 v[194:195], v[216:217], 0, s[12:13]
	s_addc_u32 s29, s29, 0
	s_add_i32 s30, s77, s9
	global_load_lds_dwordx4 v[194:195], off
	v_lshl_add_u64 v[194:195], s[28:29], 0, v[166:167]
	s_mov_b32 m0, s30
	s_nop 0
	global_load_lds_dwordx4 v[194:195], off
	v_lshl_add_u64 v[194:195], s[28:29], 0, v[162:163]
	s_add_i32 m0, s30, 0x2000
	s_nop 0
	global_load_lds_dwordx4 v[194:195], off
	v_lshl_add_u64 v[194:195], v[218:219], 0, s[12:13]
	s_mov_b32 m0, s54
	s_nop 0
	global_load_lds_dwordx4 v[194:195], off
	v_lshl_add_u64 v[194:195], v[220:221], 0, s[12:13]
	s_mov_b32 m0, s55
	s_nop 0
	global_load_lds_dwordx4 v[194:195], off
	s_waitcnt vmcnt(8)
	s_waitcnt lgkmcnt(0)
	s_barrier
	s_waitcnt lgkmcnt(0)
	v_mfma_f32_16x16x32_bf16 v[62:65], v[130:133], v[174:177], v[62:65]
	v_mfma_f32_16x16x32_bf16 v[58:61], v[138:141], v[174:177], v[58:61]
	v_mfma_f32_16x16x32_bf16 v[46:49], v[130:133], v[184:187], v[46:49]
	v_mfma_f32_16x16x32_bf16 v[42:45], v[138:141], v[184:187], v[42:45]
	v_mfma_f32_16x16x32_bf16 v[30:33], v[130:133], v[200:203], v[30:33]
	v_mfma_f32_16x16x32_bf16 v[26:29], v[138:141], v[200:203], v[26:29]
	v_mfma_f32_16x16x32_bf16 v[14:17], v[130:133], v[208:211], v[14:17]
	v_mfma_f32_16x16x32_bf16 v[10:13], v[138:141], v[208:211], v[10:13]
	v_mfma_f32_16x16x32_bf16 v[62:65], v[134:137], v[180:183], v[62:65]
	v_mfma_f32_16x16x32_bf16 v[58:61], v[142:145], v[180:183], v[58:61]
	v_mfma_f32_16x16x32_bf16 v[46:49], v[134:137], v[188:191], v[46:49]
	v_mfma_f32_16x16x32_bf16 v[42:45], v[142:145], v[188:191], v[42:45]
	v_mfma_f32_16x16x32_bf16 v[30:33], v[134:137], v[204:207], v[30:33]
	v_mfma_f32_16x16x32_bf16 v[26:29], v[142:145], v[204:207], v[26:29]
	v_mfma_f32_16x16x32_bf16 v[14:17], v[134:137], v[212:215], v[14:17]
	v_mfma_f32_16x16x32_bf16 v[10:13], v[142:145], v[212:215], v[10:13]
	v_mfma_f32_16x16x32_bf16 v[54:57], v[146:149], v[174:177], v[54:57]
	v_mfma_f32_16x16x32_bf16 v[50:53], v[154:157], v[174:177], v[50:53]
	v_mfma_f32_16x16x32_bf16 v[38:41], v[146:149], v[184:187], v[38:41]
	v_mfma_f32_16x16x32_bf16 v[34:37], v[154:157], v[184:187], v[34:37]
	v_mfma_f32_16x16x32_bf16 v[22:25], v[146:149], v[200:203], v[22:25]
	v_mfma_f32_16x16x32_bf16 v[18:21], v[154:157], v[200:203], v[18:21]
	v_mfma_f32_16x16x32_bf16 v[6:9], v[146:149], v[208:211], v[6:9]
	v_mfma_f32_16x16x32_bf16 v[2:5], v[154:157], v[208:211], v[2:5]
	v_mfma_f32_16x16x32_bf16 v[54:57], v[150:153], v[180:183], v[54:57]
	v_mfma_f32_16x16x32_bf16 v[50:53], v[158:161], v[180:183], v[50:53]
	v_mfma_f32_16x16x32_bf16 v[38:41], v[150:153], v[188:191], v[38:41]
	v_mfma_f32_16x16x32_bf16 v[34:37], v[158:161], v[188:191], v[34:37]
	v_mfma_f32_16x16x32_bf16 v[22:25], v[150:153], v[204:207], v[22:25]
	v_mfma_f32_16x16x32_bf16 v[18:21], v[158:161], v[204:207], v[18:21]
	v_mfma_f32_16x16x32_bf16 v[6:9], v[150:153], v[212:215], v[6:9]
	v_mfma_f32_16x16x32_bf16 v[2:5], v[158:161], v[212:215], v[2:5]
	s_barrier
	s_add_i32 s50, s50, 2
	s_add_u32 s0, s0, 0x100
	s_addc_u32 s1, s1, 0
	s_add_u32 s41, s41, 0x100
	s_addc_u32 s43, s43, 0
	s_cmp_gt_u32 s50, 61
	s_cbranch_scc0 .LBB0_230
	s_and_b64 vcc, exec, s[22:23]
	s_cbranch_vccz .LBB0_233
	s_barrier

.LBB0_300:
	s_add_u32 s100, s0, 0xfff80000
	s_addc_u32 s101, s1, -1
	s_add_u32 s28, s0, 0xfff80080
	s_addc_u32 s29, s1, -1
	s_add_i32 s42, 0, 0x10000
	s_cmp_eq_u32 s41, 28
	s_cselect_b32 s31, s18, s29
	s_cselect_b32 s30, s19, s28
	v_add_u32_e32 v0, s42, v199
	s_cselect_b32 s29, s27, s40
	s_cselect_b32 s28, s34, s35
	s_add_i32 s49, 0, 0x14000
	ds_read_b128 v[2:5], v0
	ds_read_b128 v[6:9], v0 offset:1024
	ds_read_b128 v[10:13], v0 offset:2048
	ds_read_b128 v[14:17], v0 offset:3072
	v_add_u32_e32 v0, s49, v199
	ds_read_b128 v[146:149], v0
	ds_read_b128 v[150:153], v0 offset:1024
	ds_read_b128 v[154:157], v0 offset:2048
	ds_read_b128 v[158:161], v0 offset:3072
	v_lshl_add_u64 v[194:195], s[100:101], 0, v[162:163]
	s_mov_b32 m0, s15
	ds_read_b128 v[174:177], v250
	ds_read_b128 v[178:181], v250 offset:1024
	ds_read_b128 v[182:185], v250 offset:2048
	ds_read_b128 v[186:189], v250 offset:3072
	ds_read_b128 v[190:193], v250 offset:4096
	ds_read_b128 v[200:203], v250 offset:5120
	ds_read_b128 v[204:207], v250 offset:6144
	ds_read_b128 v[208:211], v250 offset:7168
	global_load_lds_dwordx4 v[194:195], off
	v_lshl_add_u64 v[194:195], s[100:101], 0, v[166:167]
	s_mov_b32 m0, s88
	s_nop 0
	global_load_lds_dwordx4 v[194:195], off
	v_lshl_add_u64 v[194:195], s[0:1], 0, v[170:171]
	s_add_i32 m0, s21, 0xc000
	s_nop 0
	global_load_lds_dwordx4 v[194:195], off
	v_lshl_add_u64 v[194:195], s[0:1], 0, v[172:173]
	s_add_i32 m0, s21, 0xe000
	s_nop 0
	global_load_lds_dwordx4 v[194:195], off
	s_waitcnt vmcnt(8)
	s_waitcnt lgkmcnt(0)
	s_barrier
	s_waitcnt lgkmcnt(0)
	v_mfma_i32_16x16x64_i8 v[142:145], v[2:5], v[174:177], v[142:145]
	v_mfma_i32_16x16x64_i8 v[138:141], v[10:13], v[174:177], v[138:141]
	v_mfma_i32_16x16x64_i8 v[134:137], v[2:5], v[182:185], v[134:137]
	v_mfma_i32_16x16x64_i8 v[130:133], v[10:13], v[182:185], v[130:133]
	v_mfma_i32_16x16x64_i8 v[122:125], v[2:5], v[190:193], v[122:125]
	v_mfma_i32_16x16x64_i8 v[114:117], v[10:13], v[190:193], v[114:117]
	v_mfma_i32_16x16x64_i8 v[106:109], v[2:5], v[204:207], v[106:109]
	v_mfma_i32_16x16x64_i8 v[98:101], v[10:13], v[204:207], v[98:101]
	v_mfma_i32_16x16x64_i8 v[142:145], v[6:9], v[178:181], v[142:145]
	v_mfma_i32_16x16x64_i8 v[138:141], v[14:17], v[178:181], v[138:141]
	v_mfma_i32_16x16x64_i8 v[134:137], v[6:9], v[186:189], v[134:137]
	v_mfma_i32_16x16x64_i8 v[130:133], v[14:17], v[186:189], v[130:133]
	v_mfma_i32_16x16x64_i8 v[122:125], v[6:9], v[200:203], v[122:125]
	v_mfma_i32_16x16x64_i8 v[114:117], v[14:17], v[200:203], v[114:117]
	v_mfma_i32_16x16x64_i8 v[106:109], v[6:9], v[208:211], v[106:109]
	v_mfma_i32_16x16x64_i8 v[98:101], v[14:17], v[208:211], v[98:101]
	v_mfma_i32_16x16x64_i8 v[126:129], v[146:149], v[174:177], v[126:129]
	v_mfma_i32_16x16x64_i8 v[118:121], v[154:157], v[174:177], v[118:121]
	v_mfma_i32_16x16x64_i8 v[110:113], v[146:149], v[182:185], v[110:113]
	v_mfma_i32_16x16x64_i8 v[102:105], v[154:157], v[182:185], v[102:105]
	v_mfma_i32_16x16x64_i8 v[94:97], v[146:149], v[190:193], v[94:97]
	v_mfma_i32_16x16x64_i8 v[90:93], v[154:157], v[190:193], v[90:93]
	v_mfma_i32_16x16x64_i8 v[86:89], v[146:149], v[204:207], v[86:89]
	v_mfma_i32_16x16x64_i8 v[82:85], v[154:157], v[204:207], v[82:85]
	v_mfma_i32_16x16x64_i8 v[126:129], v[150:153], v[178:181], v[126:129]
	v_mfma_i32_16x16x64_i8 v[118:121], v[158:161], v[178:181], v[118:121]
	v_mfma_i32_16x16x64_i8 v[110:113], v[150:153], v[186:189], v[110:113]
	v_mfma_i32_16x16x64_i8 v[102:105], v[158:161], v[186:189], v[102:105]
	v_mfma_i32_16x16x64_i8 v[94:97], v[150:153], v[200:203], v[94:97]
	v_mfma_i32_16x16x64_i8 v[90:93], v[158:161], v[200:203], v[90:93]
	v_mfma_i32_16x16x64_i8 v[86:89], v[150:153], v[208:211], v[86:89]
	v_mfma_i32_16x16x64_i8 v[82:85], v[158:161], v[208:211], v[82:85]
	s_barrier
	s_add_i32 s42, s42, s81
	v_lshl_add_u64 v[194:195], s[28:29], 0, v[164:165]
	s_mov_b32 m0, s42
	ds_read_b128 v[174:177], v250 offset:16384
	ds_read_b128 v[178:181], v250 offset:17408
	ds_read_b128 v[182:185], v250 offset:18432
	ds_read_b128 v[186:189], v250 offset:19456
	ds_read_b128 v[190:193], v250 offset:20480
	ds_read_b128 v[200:203], v250 offset:21504
	ds_read_b128 v[204:207], v250 offset:22528
	ds_read_b128 v[208:211], v250 offset:23552
	global_load_lds_dwordx4 v[194:195], off
	s_add_i32 m0, s42, 0x2000
	s_add_u32 s42, s28, 0x80000
	v_lshl_add_u64 v[212:213], s[28:29], 0, v[168:169]
	s_addc_u32 s43, s29, 0
	s_add_i32 s49, s49, s81
	global_load_lds_dwordx4 v[212:213], off
	v_lshl_add_u64 v[214:215], s[42:43], 0, v[164:165]
	s_mov_b32 m0, s49
	v_lshl_add_u64 v[216:217], s[30:31], 0, v[166:167]
	global_load_lds_dwordx4 v[214:215], off
	v_lshl_add_u64 v[214:215], s[42:43], 0, v[168:169]
	s_add_i32 m0, s49, 0x2000
	s_nop 0
	global_load_lds_dwordx4 v[214:215], off
	v_lshl_add_u64 v[214:215], s[30:31], 0, v[162:163]
	s_waitcnt vmcnt(6)
	s_waitcnt lgkmcnt(0)
	s_barrier
	s_waitcnt lgkmcnt(0)
	v_mfma_i32_16x16x64_i8 v[78:81], v[2:5], v[174:177], v[78:81]
	v_mfma_i32_16x16x64_i8 v[74:77], v[10:13], v[174:177], v[74:77]
	v_mfma_i32_16x16x64_i8 v[70:73], v[2:5], v[182:185], v[70:73]
	v_mfma_i32_16x16x64_i8 v[66:69], v[10:13], v[182:185], v[66:69]
	v_mfma_i32_16x16x64_i8 v[54:57], v[2:5], v[190:193], v[54:57]
	v_mfma_i32_16x16x64_i8 v[50:53], v[10:13], v[190:193], v[50:53]
	v_mfma_i32_16x16x64_i8 v[2:5], v[2:5], v[204:207], v[38:41]
	v_mfma_i32_16x16x64_i8 v[78:81], v[6:9], v[178:181], v[78:81]
	v_mfma_i32_16x16x64_i8 v[74:77], v[14:17], v[178:181], v[74:77]
	v_mfma_i32_16x16x64_i8 v[70:73], v[6:9], v[186:189], v[70:73]
	v_mfma_i32_16x16x64_i8 v[66:69], v[14:17], v[186:189], v[66:69]
	v_mfma_i32_16x16x64_i8 v[54:57], v[6:9], v[200:203], v[54:57]
	v_mfma_i32_16x16x64_i8 v[50:53], v[14:17], v[200:203], v[50:53]
	v_mfma_i32_16x16x64_i8 v[2:5], v[6:9], v[208:211], v[2:5]
	v_mfma_i32_16x16x64_i8 v[6:9], v[10:13], v[204:207], v[34:37]
	v_mfma_i32_16x16x64_i8 v[6:9], v[14:17], v[208:211], v[6:9]
	v_mfma_i32_16x16x64_i8 v[34:37], v[146:149], v[182:185], v[46:49]
	v_mfma_i32_16x16x64_i8 v[46:49], v[150:153], v[186:189], v[34:37]
	v_mfma_i32_16x16x64_i8 v[34:37], v[154:157], v[182:185], v[42:45]
	v_mfma_i32_16x16x64_i8 v[30:33], v[146:149], v[190:193], v[30:33]
	v_mfma_i32_16x16x64_i8 v[26:29], v[154:157], v[190:193], v[26:29]
	v_mfma_i32_16x16x64_i8 v[22:25], v[146:149], v[204:207], v[22:25]
	v_mfma_i32_16x16x64_i8 v[18:21], v[154:157], v[204:207], v[18:21]
	v_mfma_i32_16x16x64_i8 v[10:13], v[146:149], v[174:177], v[62:65]
	v_mfma_i32_16x16x64_i8 v[14:17], v[154:157], v[174:177], v[58:61]
	v_mfma_i32_16x16x64_i8 v[42:45], v[158:161], v[186:189], v[34:37]
	v_mfma_i32_16x16x64_i8 v[30:33], v[150:153], v[200:203], v[30:33]
	v_mfma_i32_16x16x64_i8 v[26:29], v[158:161], v[200:203], v[26:29]
	v_mfma_i32_16x16x64_i8 v[22:25], v[150:153], v[208:211], v[22:25]
	v_mfma_i32_16x16x64_i8 v[18:21], v[158:161], v[208:211], v[18:21]
	v_mfma_i32_16x16x64_i8 v[10:13], v[150:153], v[178:181], v[10:13]
	v_mfma_i32_16x16x64_i8 v[14:17], v[158:161], v[178:181], v[14:17]
	s_barrier
	s_add_i32 s42, 0, 0x18000
	v_add_u32_e32 v0, s42, v199
	s_add_i32 s43, 0, 0x1c000
	ds_read_b128 v[34:37], v0
	ds_read_b128 v[38:41], v0 offset:1024
	ds_read_b128 v[58:61], v0 offset:2048
	ds_read_b128 v[62:65], v0 offset:3072
	v_add_u32_e32 v0, s43, v199
	ds_read_b128 v[146:149], v0
	ds_read_b128 v[150:153], v0 offset:1024
	ds_read_b128 v[154:157], v0 offset:2048
	ds_read_b128 v[158:161], v0 offset:3072
	s_add_u32 s30, s30, 0x80000
	s_addc_u32 s31, s31, 0
	s_mov_b32 m0, s21
	v_lshl_add_u64 v[218:219], s[30:31], 0, v[162:163]
	ds_read_b128 v[174:177], v250 offset:32768
	ds_read_b128 v[178:181], v250 offset:33792
	ds_read_b128 v[182:185], v250 offset:34816
	ds_read_b128 v[186:189], v250 offset:35840
	ds_read_b128 v[190:193], v250 offset:36864
	ds_read_b128 v[200:203], v250 offset:37888
	ds_read_b128 v[204:207], v250 offset:38912
	ds_read_b128 v[208:211], v250 offset:39936
	global_load_lds_dwordx4 v[214:215], off
	s_mov_b32 m0, s57
	s_nop 0
	global_load_lds_dwordx4 v[216:217], off
	s_mov_b32 m0, s73
	s_nop 0
	global_load_lds_dwordx4 v[218:219], off
	v_lshl_add_u64 v[218:219], s[30:31], 0, v[166:167]
	s_mov_b32 m0, s76
	s_nop 0
	global_load_lds_dwordx4 v[218:219], off
	s_waitcnt vmcnt(8)
	s_waitcnt lgkmcnt(0)
	s_barrier
	s_waitcnt lgkmcnt(0)
	v_mfma_i32_16x16x64_i8 v[142:145], v[34:37], v[174:177], v[142:145]
	v_mfma_i32_16x16x64_i8 v[138:141], v[58:61], v[174:177], v[138:141]
	v_mfma_i32_16x16x64_i8 v[134:137], v[34:37], v[182:185], v[134:137]
	v_mfma_i32_16x16x64_i8 v[130:133], v[58:61], v[182:185], v[130:133]
	v_mfma_i32_16x16x64_i8 v[122:125], v[34:37], v[190:193], v[122:125]
	v_mfma_i32_16x16x64_i8 v[114:117], v[58:61], v[190:193], v[114:117]
	v_mfma_i32_16x16x64_i8 v[106:109], v[34:37], v[204:207], v[106:109]
	v_mfma_i32_16x16x64_i8 v[98:101], v[58:61], v[204:207], v[98:101]
	v_mfma_i32_16x16x64_i8 v[142:145], v[38:41], v[178:181], v[142:145]
	v_mfma_i32_16x16x64_i8 v[138:141], v[62:65], v[178:181], v[138:141]
	v_mfma_i32_16x16x64_i8 v[134:137], v[38:41], v[186:189], v[134:137]
	v_mfma_i32_16x16x64_i8 v[130:133], v[62:65], v[186:189], v[130:133]
	v_mfma_i32_16x16x64_i8 v[122:125], v[38:41], v[200:203], v[122:125]
	v_mfma_i32_16x16x64_i8 v[114:117], v[62:65], v[200:203], v[114:117]
	v_mfma_i32_16x16x64_i8 v[106:109], v[38:41], v[208:211], v[106:109]
	v_mfma_i32_16x16x64_i8 v[98:101], v[62:65], v[208:211], v[98:101]
	v_mfma_i32_16x16x64_i8 v[126:129], v[146:149], v[174:177], v[126:129]
	v_mfma_i32_16x16x64_i8 v[118:121], v[154:157], v[174:177], v[118:121]
	v_mfma_i32_16x16x64_i8 v[110:113], v[146:149], v[182:185], v[110:113]
	v_mfma_i32_16x16x64_i8 v[102:105], v[154:157], v[182:185], v[102:105]
	v_mfma_i32_16x16x64_i8 v[94:97], v[146:149], v[190:193], v[94:97]
	v_mfma_i32_16x16x64_i8 v[90:93], v[154:157], v[190:193], v[90:93]
	v_mfma_i32_16x16x64_i8 v[86:89], v[146:149], v[204:207], v[86:89]
	v_mfma_i32_16x16x64_i8 v[82:85], v[154:157], v[204:207], v[82:85]
	v_mfma_i32_16x16x64_i8 v[126:129], v[150:153], v[178:181], v[126:129]
	v_mfma_i32_16x16x64_i8 v[118:121], v[158:161], v[178:181], v[118:121]
	v_mfma_i32_16x16x64_i8 v[110:113], v[150:153], v[186:189], v[110:113]
	v_mfma_i32_16x16x64_i8 v[102:105], v[158:161], v[186:189], v[102:105]
	v_mfma_i32_16x16x64_i8 v[94:97], v[150:153], v[200:203], v[94:97]
	v_mfma_i32_16x16x64_i8 v[90:93], v[158:161], v[200:203], v[90:93]
	v_mfma_i32_16x16x64_i8 v[86:89], v[150:153], v[208:211], v[86:89]
	v_mfma_i32_16x16x64_i8 v[82:85], v[158:161], v[208:211], v[82:85]
	s_barrier
	s_add_i32 s30, s42, s81
	v_lshl_add_u64 v[194:195], v[194:195], 0, s[12:13]
	s_mov_b32 m0, s30
	ds_read_b128 v[174:177], v250 offset:49152
	ds_read_b128 v[178:181], v250 offset:50176
	ds_read_b128 v[182:185], v250 offset:51200
	ds_read_b128 v[186:189], v250 offset:52224
	ds_read_b128 v[190:193], v250 offset:53248
	ds_read_b128 v[200:203], v250 offset:54272
	ds_read_b128 v[204:207], v250 offset:55296
	ds_read_b128 v[208:211], v250 offset:56320
	global_load_lds_dwordx4 v[194:195], off
	s_add_i32 m0, s30, 0x2000
	s_add_u32 s28, s28, 0x80080
	v_lshl_add_u64 v[194:195], v[212:213], 0, s[12:13]
	s_addc_u32 s29, s29, 0
	s_add_i32 s30, s43, s81
	global_load_lds_dwordx4 v[194:195], off
	v_lshl_add_u64 v[194:195], s[28:29], 0, v[164:165]
	s_mov_b32 m0, s30
	s_nop 0
	global_load_lds_dwordx4 v[194:195], off
	v_lshl_add_u64 v[194:195], s[28:29], 0, v[168:169]
	s_add_i32 m0, s30, 0x2000
	s_nop 0
	global_load_lds_dwordx4 v[194:195], off
	s_waitcnt vmcnt(6)
	s_waitcnt lgkmcnt(0)
	s_barrier
	s_waitcnt lgkmcnt(0)
	v_mfma_i32_16x16x64_i8 v[78:81], v[34:37], v[174:177], v[78:81]
	v_mfma_i32_16x16x64_i8 v[70:73], v[34:37], v[182:185], v[70:73]
	v_mfma_i32_16x16x64_i8 v[54:57], v[34:37], v[190:193], v[54:57]
	v_mfma_i32_16x16x64_i8 v[2:5], v[34:37], v[204:207], v[2:5]
	v_mfma_i32_16x16x64_i8 v[78:81], v[38:41], v[178:181], v[78:81]
	v_mfma_i32_16x16x64_i8 v[74:77], v[58:61], v[174:177], v[74:77]
	v_mfma_i32_16x16x64_i8 v[70:73], v[38:41], v[186:189], v[70:73]
	v_mfma_i32_16x16x64_i8 v[66:69], v[58:61], v[182:185], v[66:69]
	v_mfma_i32_16x16x64_i8 v[54:57], v[38:41], v[200:203], v[54:57]
	v_mfma_i32_16x16x64_i8 v[50:53], v[58:61], v[190:193], v[50:53]
	v_mfma_i32_16x16x64_i8 v[38:41], v[38:41], v[208:211], v[2:5]
	v_mfma_i32_16x16x64_i8 v[2:5], v[58:61], v[204:207], v[6:9]
	v_mfma_i32_16x16x64_i8 v[74:77], v[62:65], v[178:181], v[74:77]
	v_mfma_i32_16x16x64_i8 v[66:69], v[62:65], v[186:189], v[66:69]
	v_mfma_i32_16x16x64_i8 v[50:53], v[62:65], v[200:203], v[50:53]
	v_mfma_i32_16x16x64_i8 v[34:37], v[62:65], v[208:211], v[2:5]
	v_mfma_i32_16x16x64_i8 v[2:5], v[146:149], v[174:177], v[10:13]
	v_mfma_i32_16x16x64_i8 v[62:65], v[150:153], v[178:181], v[2:5]
	v_mfma_i32_16x16x64_i8 v[2:5], v[154:157], v[174:177], v[14:17]
	v_mfma_i32_16x16x64_i8 v[58:61], v[158:161], v[178:181], v[2:5]
	v_mfma_i32_16x16x64_i8 v[2:5], v[146:149], v[182:185], v[46:49]
	v_mfma_i32_16x16x64_i8 v[46:49], v[150:153], v[186:189], v[2:5]
	v_mfma_i32_16x16x64_i8 v[2:5], v[154:157], v[182:185], v[42:45]
	v_mfma_i32_16x16x64_i8 v[42:45], v[158:161], v[186:189], v[2:5]
	v_mfma_i32_16x16x64_i8 v[2:5], v[146:149], v[190:193], v[30:33]
	v_mfma_i32_16x16x64_i8 v[30:33], v[150:153], v[200:203], v[2:5]
	v_mfma_i32_16x16x64_i8 v[2:5], v[154:157], v[190:193], v[26:29]
	v_mfma_i32_16x16x64_i8 v[26:29], v[158:161], v[200:203], v[2:5]
	v_mfma_i32_16x16x64_i8 v[2:5], v[146:149], v[204:207], v[22:25]
	v_mfma_i32_16x16x64_i8 v[22:25], v[150:153], v[208:211], v[2:5]
	v_mfma_i32_16x16x64_i8 v[2:5], v[154:157], v[204:207], v[18:21]
	v_mfma_i32_16x16x64_i8 v[18:21], v[158:161], v[208:211], v[2:5]
	s_barrier
	s_add_i32 s41, s41, 2
	s_add_u32 s0, s0, 0x100
	s_addc_u32 s1, s1, 0
	s_add_u32 s35, s35, 0x100
	s_addc_u32 s40, s40, 0
	s_cmp_gt_u32 s41, 29
	s_cbranch_scc0 .LBB0_300
	s_and_b64 vcc, exec, s[52:53]
	s_cbranch_vccz .LBB0_303
	s_barrier

.LBB0_577:
	s_add_u32 s34, s30, 0xfff80080
	s_addc_u32 s35, s31, -1
	s_add_i32 s66, 0, 0x10000
	s_cmp_eq_u32 s57, 28
	s_cselect_b32 s43, s19, s35
	s_cselect_b32 s42, s23, s34
	v_add_u32_e32 v0, s66, v228
	s_cselect_b32 s35, s25, s56
	s_cselect_b32 s34, s54, s55
	s_add_i32 s73, 0, 0x14000
	ds_read_b128 v[132:135], v0
	ds_read_b128 v[136:139], v0 offset:1024
	ds_read_b128 v[140:143], v0 offset:2048
	ds_read_b128 v[144:147], v0 offset:3072
	v_add_u32_e32 v0, s73, v228
	ds_read_b128 v[148:151], v0
	ds_read_b128 v[152:155], v0 offset:1024
	ds_read_b128 v[156:159], v0 offset:2048
	ds_read_b128 v[160:163], v0 offset:3072
	v_lshl_add_u64 v[2:3], s[30:31], 0, v[208:209]
	s_add_i32 m0, s46, 0xc000
	ds_read_b128 v[164:167], v230
	ds_read_b128 v[168:171], v230 offset:1024
	ds_read_b128 v[172:175], v230 offset:2048
	ds_read_b128 v[176:179], v230 offset:3072
	ds_read_b128 v[180:183], v230 offset:4096
	ds_read_b128 v[184:187], v230 offset:5120
	ds_read_b128 v[188:191], v230 offset:6144
	ds_read_b128 v[192:195], v230 offset:7168
	global_load_lds_dwordx4 v[2:3], off
	v_lshl_add_u64 v[2:3], s[30:31], 0, v[210:211]
	s_add_i32 m0, s46, 0xe000
	s_nop 0
	global_load_lds_dwordx4 v[2:3], off
	s_waitcnt vmcnt(8)
	s_waitcnt lgkmcnt(0)
	s_barrier
	s_waitcnt lgkmcnt(0)
	v_mfma_f32_16x16x32_bf16 v[128:131], v[132:135], v[164:167], v[128:131]
	v_mfma_f32_16x16x32_bf16 v[124:127], v[140:143], v[164:167], v[124:127]
	v_mfma_f32_16x16x32_bf16 v[120:123], v[132:135], v[172:175], v[120:123]
	v_mfma_f32_16x16x32_bf16 v[116:119], v[140:143], v[172:175], v[116:119]
	v_mfma_f32_16x16x32_bf16 v[112:115], v[132:135], v[180:183], v[112:115]
	v_mfma_f32_16x16x32_bf16 v[108:111], v[140:143], v[180:183], v[108:111]
	v_mfma_f32_16x16x32_bf16 v[104:107], v[132:135], v[188:191], v[104:107]
	v_mfma_f32_16x16x32_bf16 v[100:103], v[140:143], v[188:191], v[100:103]
	v_mfma_f32_16x16x32_bf16 v[128:131], v[136:139], v[168:171], v[128:131]
	v_mfma_f32_16x16x32_bf16 v[124:127], v[144:147], v[168:171], v[124:127]
	v_mfma_f32_16x16x32_bf16 v[120:123], v[136:139], v[176:179], v[120:123]
	v_mfma_f32_16x16x32_bf16 v[116:119], v[144:147], v[176:179], v[116:119]
	v_mfma_f32_16x16x32_bf16 v[112:115], v[136:139], v[184:187], v[112:115]
	v_mfma_f32_16x16x32_bf16 v[108:111], v[144:147], v[184:187], v[108:111]
	v_mfma_f32_16x16x32_bf16 v[104:107], v[136:139], v[192:195], v[104:107]
	v_mfma_f32_16x16x32_bf16 v[100:103], v[144:147], v[192:195], v[100:103]
	v_mfma_f32_16x16x32_bf16 v[96:99], v[148:151], v[164:167], v[96:99]
	v_mfma_f32_16x16x32_bf16 v[92:95], v[156:159], v[164:167], v[92:95]
	v_mfma_f32_16x16x32_bf16 v[88:91], v[148:151], v[172:175], v[88:91]
	v_mfma_f32_16x16x32_bf16 v[84:87], v[156:159], v[172:175], v[84:87]
	v_mfma_f32_16x16x32_bf16 v[80:83], v[148:151], v[180:183], v[80:83]
	v_mfma_f32_16x16x32_bf16 v[76:79], v[156:159], v[180:183], v[76:79]
	v_mfma_f32_16x16x32_bf16 v[72:75], v[148:151], v[188:191], v[72:75]
	v_mfma_f32_16x16x32_bf16 v[68:71], v[156:159], v[188:191], v[68:71]
	v_mfma_f32_16x16x32_bf16 v[96:99], v[152:155], v[168:171], v[96:99]
	v_mfma_f32_16x16x32_bf16 v[92:95], v[160:163], v[168:171], v[92:95]
	v_mfma_f32_16x16x32_bf16 v[88:91], v[152:155], v[176:179], v[88:91]
	v_mfma_f32_16x16x32_bf16 v[84:87], v[160:163], v[176:179], v[84:87]
	v_mfma_f32_16x16x32_bf16 v[80:83], v[152:155], v[184:187], v[80:83]
	v_mfma_f32_16x16x32_bf16 v[76:79], v[160:163], v[184:187], v[76:79]
	v_mfma_f32_16x16x32_bf16 v[72:75], v[152:155], v[192:195], v[72:75]
	v_mfma_f32_16x16x32_bf16 v[68:71], v[160:163], v[192:195], v[68:71]
	s_barrier
	s_add_i32 s66, s66, s15
	v_lshl_add_u64 v[212:213], s[34:35], 0, v[204:205]
	s_mov_b32 m0, s66
	ds_read_b128 v[164:167], v230 offset:16384
	ds_read_b128 v[168:171], v230 offset:17408
	ds_read_b128 v[172:175], v230 offset:18432
	ds_read_b128 v[176:179], v230 offset:19456
	ds_read_b128 v[180:183], v230 offset:20480
	ds_read_b128 v[184:187], v230 offset:21504
	ds_read_b128 v[188:191], v230 offset:22528
	ds_read_b128 v[192:195], v230 offset:23552
	global_load_lds_dwordx4 v[212:213], off
	s_add_i32 m0, s66, 0x2000
	s_add_u32 s66, s34, 0x80000
	v_lshl_add_u64 v[214:215], s[34:35], 0, v[200:201]
	s_addc_u32 s67, s35, 0
	s_add_i32 s73, s73, s15
	global_load_lds_dwordx4 v[214:215], off
	v_lshl_add_u64 v[2:3], s[66:67], 0, v[204:205]
	s_mov_b32 m0, s73
	v_lshl_add_u64 v[216:217], s[42:43], 0, v[206:207]
	global_load_lds_dwordx4 v[2:3], off
	v_lshl_add_u64 v[2:3], s[66:67], 0, v[200:201]
	s_add_i32 m0, s73, 0x2000
	v_lshl_add_u64 v[218:219], s[42:43], 0, v[202:203]
	global_load_lds_dwordx4 v[2:3], off
	s_mov_b32 m0, s46
	s_nop 0
	global_load_lds_dwordx4 v[216:217], off
	s_mov_b32 m0, s47
	s_nop 0
	global_load_lds_dwordx4 v[218:219], off
	s_waitcnt vmcnt(8)
	s_waitcnt lgkmcnt(0)
	s_barrier
	s_waitcnt lgkmcnt(0)
	v_mfma_f32_16x16x32_bf16 v[64:67], v[132:135], v[164:167], v[64:67]
	v_mfma_f32_16x16x32_bf16 v[60:63], v[140:143], v[164:167], v[60:63]
	v_mfma_f32_16x16x32_bf16 v[56:59], v[132:135], v[172:175], v[56:59]
	v_mfma_f32_16x16x32_bf16 v[52:55], v[140:143], v[172:175], v[52:55]
	v_mfma_f32_16x16x32_bf16 v[48:51], v[132:135], v[180:183], v[48:51]
	v_mfma_f32_16x16x32_bf16 v[44:47], v[140:143], v[180:183], v[44:47]
	v_mfma_f32_16x16x32_bf16 v[40:43], v[132:135], v[188:191], v[40:43]
	v_mfma_f32_16x16x32_bf16 v[36:39], v[140:143], v[188:191], v[36:39]
	v_mfma_f32_16x16x32_bf16 v[64:67], v[136:139], v[168:171], v[64:67]
	v_mfma_f32_16x16x32_bf16 v[60:63], v[144:147], v[168:171], v[60:63]
	v_mfma_f32_16x16x32_bf16 v[56:59], v[136:139], v[176:179], v[56:59]
	v_mfma_f32_16x16x32_bf16 v[52:55], v[144:147], v[176:179], v[52:55]
	v_mfma_f32_16x16x32_bf16 v[48:51], v[136:139], v[184:187], v[48:51]
	v_mfma_f32_16x16x32_bf16 v[44:47], v[144:147], v[184:187], v[44:47]
	v_mfma_f32_16x16x32_bf16 v[40:43], v[136:139], v[192:195], v[40:43]
	v_mfma_f32_16x16x32_bf16 v[36:39], v[144:147], v[192:195], v[36:39]
	v_mfma_f32_16x16x32_bf16 v[32:35], v[148:151], v[164:167], v[32:35]
	v_mfma_f32_16x16x32_bf16 v[28:31], v[156:159], v[164:167], v[28:31]
	v_mfma_f32_16x16x32_bf16 v[24:27], v[148:151], v[172:175], v[24:27]
	v_mfma_f32_16x16x32_bf16 v[20:23], v[156:159], v[172:175], v[20:23]
	v_mfma_f32_16x16x32_bf16 v[16:19], v[148:151], v[180:183], v[16:19]
	v_mfma_f32_16x16x32_bf16 v[12:15], v[156:159], v[180:183], v[12:15]
	v_mfma_f32_16x16x32_bf16 v[8:11], v[148:151], v[188:191], v[8:11]
	v_mfma_f32_16x16x32_bf16 v[2:5], v[156:159], v[188:191], v[4:7]
	v_mfma_f32_16x16x32_bf16 v[32:35], v[152:155], v[168:171], v[32:35]
	v_mfma_f32_16x16x32_bf16 v[28:31], v[160:163], v[168:171], v[28:31]
	v_mfma_f32_16x16x32_bf16 v[24:27], v[152:155], v[176:179], v[24:27]
	v_mfma_f32_16x16x32_bf16 v[20:23], v[160:163], v[176:179], v[20:23]
	v_mfma_f32_16x16x32_bf16 v[16:19], v[152:155], v[184:187], v[16:19]
	v_mfma_f32_16x16x32_bf16 v[12:15], v[160:163], v[184:187], v[12:15]
	v_mfma_f32_16x16x32_bf16 v[8:11], v[152:155], v[192:195], v[8:11]
	v_mfma_f32_16x16x32_bf16 v[2:5], v[160:163], v[192:195], v[2:5]
	s_barrier
	s_add_i32 s66, 0, 0x18000
	v_add_u32_e32 v0, s66, v228
	s_add_i32 s67, 0, 0x1c000
	ds_read_b128 v[132:135], v0
	ds_read_b128 v[136:139], v0 offset:1024
	ds_read_b128 v[140:143], v0 offset:2048
	ds_read_b128 v[144:147], v0 offset:3072
	v_add_u32_e32 v0, s67, v228
	ds_read_b128 v[148:151], v0
	ds_read_b128 v[152:155], v0 offset:1024
	ds_read_b128 v[156:159], v0 offset:2048
	ds_read_b128 v[160:163], v0 offset:3072
	s_add_u32 s42, s42, 0x80000
	s_addc_u32 s43, s43, 0
	s_mov_b32 m0, s48
	v_lshl_add_u64 v[6:7], s[42:43], 0, v[206:207]
	ds_read_b128 v[164:167], v230 offset:32768
	ds_read_b128 v[168:171], v230 offset:33792
	ds_read_b128 v[172:175], v230 offset:34816
	ds_read_b128 v[176:179], v230 offset:35840
	ds_read_b128 v[180:183], v230 offset:36864
	ds_read_b128 v[184:187], v230 offset:37888
	ds_read_b128 v[188:191], v230 offset:38912
	ds_read_b128 v[192:195], v230 offset:39936
	global_load_lds_dwordx4 v[6:7], off
	v_lshl_add_u64 v[6:7], s[42:43], 0, v[202:203]
	s_mov_b32 m0, s49
	s_nop 0
	global_load_lds_dwordx4 v[6:7], off
	s_waitcnt vmcnt(8)
	s_waitcnt lgkmcnt(0)
	s_barrier
	s_waitcnt lgkmcnt(0)
	v_mfma_f32_16x16x32_bf16 v[128:131], v[132:135], v[164:167], v[128:131]
	v_mfma_f32_16x16x32_bf16 v[124:127], v[140:143], v[164:167], v[124:127]
	v_mfma_f32_16x16x32_bf16 v[120:123], v[132:135], v[172:175], v[120:123]
	v_mfma_f32_16x16x32_bf16 v[116:119], v[140:143], v[172:175], v[116:119]
	v_mfma_f32_16x16x32_bf16 v[112:115], v[132:135], v[180:183], v[112:115]
	v_mfma_f32_16x16x32_bf16 v[108:111], v[140:143], v[180:183], v[108:111]
	v_mfma_f32_16x16x32_bf16 v[104:107], v[132:135], v[188:191], v[104:107]
	v_mfma_f32_16x16x32_bf16 v[100:103], v[140:143], v[188:191], v[100:103]
	v_mfma_f32_16x16x32_bf16 v[128:131], v[136:139], v[168:171], v[128:131]
	v_mfma_f32_16x16x32_bf16 v[124:127], v[144:147], v[168:171], v[124:127]
	v_mfma_f32_16x16x32_bf16 v[120:123], v[136:139], v[176:179], v[120:123]
	v_mfma_f32_16x16x32_bf16 v[116:119], v[144:147], v[176:179], v[116:119]
	v_mfma_f32_16x16x32_bf16 v[112:115], v[136:139], v[184:187], v[112:115]
	v_mfma_f32_16x16x32_bf16 v[108:111], v[144:147], v[184:187], v[108:111]
	v_mfma_f32_16x16x32_bf16 v[104:107], v[136:139], v[192:195], v[104:107]
	v_mfma_f32_16x16x32_bf16 v[100:103], v[144:147], v[192:195], v[100:103]
	v_mfma_f32_16x16x32_bf16 v[96:99], v[148:151], v[164:167], v[96:99]
	v_mfma_f32_16x16x32_bf16 v[92:95], v[156:159], v[164:167], v[92:95]
	v_mfma_f32_16x16x32_bf16 v[88:91], v[148:151], v[172:175], v[88:91]
	v_mfma_f32_16x16x32_bf16 v[84:87], v[156:159], v[172:175], v[84:87]
	v_mfma_f32_16x16x32_bf16 v[80:83], v[148:151], v[180:183], v[80:83]
	v_mfma_f32_16x16x32_bf16 v[76:79], v[156:159], v[180:183], v[76:79]
	v_mfma_f32_16x16x32_bf16 v[72:75], v[148:151], v[188:191], v[72:75]
	v_mfma_f32_16x16x32_bf16 v[68:71], v[156:159], v[188:191], v[68:71]
	v_mfma_f32_16x16x32_bf16 v[96:99], v[152:155], v[168:171], v[96:99]
	v_mfma_f32_16x16x32_bf16 v[92:95], v[160:163], v[168:171], v[92:95]
	v_mfma_f32_16x16x32_bf16 v[88:91], v[152:155], v[176:179], v[88:91]
	v_mfma_f32_16x16x32_bf16 v[84:87], v[160:163], v[176:179], v[84:87]
	v_mfma_f32_16x16x32_bf16 v[80:83], v[152:155], v[184:187], v[80:83]
	v_mfma_f32_16x16x32_bf16 v[76:79], v[160:163], v[184:187], v[76:79]
	v_mfma_f32_16x16x32_bf16 v[72:75], v[152:155], v[192:195], v[72:75]
	v_mfma_f32_16x16x32_bf16 v[68:71], v[160:163], v[192:195], v[68:71]
	s_barrier
	s_add_i32 s42, s66, s15
	v_lshl_add_u64 v[6:7], v[212:213], 0, s[12:13]
	s_mov_b32 m0, s42
	ds_read_b128 v[164:167], v230 offset:49152
	ds_read_b128 v[168:171], v230 offset:50176
	ds_read_b128 v[172:175], v230 offset:51200
	ds_read_b128 v[176:179], v230 offset:52224
	ds_read_b128 v[180:183], v230 offset:53248
	ds_read_b128 v[184:187], v230 offset:54272
	ds_read_b128 v[188:191], v230 offset:55296
	ds_read_b128 v[192:195], v230 offset:56320
	global_load_lds_dwordx4 v[6:7], off
	s_add_i32 m0, s42, 0x2000
	s_add_u32 s34, s34, 0x80080
	v_lshl_add_u64 v[6:7], v[214:215], 0, s[12:13]
	s_addc_u32 s35, s35, 0
	s_add_i32 s42, s67, s15
	global_load_lds_dwordx4 v[6:7], off
	v_lshl_add_u64 v[6:7], s[34:35], 0, v[204:205]
	s_mov_b32 m0, s42
	s_nop 0
	global_load_lds_dwordx4 v[6:7], off
	v_lshl_add_u64 v[6:7], s[34:35], 0, v[200:201]
	s_add_i32 m0, s42, 0x2000
	s_nop 0
	global_load_lds_dwordx4 v[6:7], off
	v_lshl_add_u64 v[6:7], v[216:217], 0, s[12:13]
	s_mov_b32 m0, s50
	s_nop 0
	global_load_lds_dwordx4 v[6:7], off
	v_lshl_add_u64 v[6:7], v[218:219], 0, s[12:13]
	s_mov_b32 m0, s51
	s_nop 0
	global_load_lds_dwordx4 v[6:7], off
	s_waitcnt vmcnt(8)
	s_waitcnt lgkmcnt(0)
	s_barrier
	s_waitcnt lgkmcnt(0)
	v_mfma_f32_16x16x32_bf16 v[64:67], v[132:135], v[164:167], v[64:67]
	v_mfma_f32_16x16x32_bf16 v[60:63], v[140:143], v[164:167], v[60:63]
	v_mfma_f32_16x16x32_bf16 v[56:59], v[132:135], v[172:175], v[56:59]
	v_mfma_f32_16x16x32_bf16 v[52:55], v[140:143], v[172:175], v[52:55]
	v_mfma_f32_16x16x32_bf16 v[48:51], v[132:135], v[180:183], v[48:51]
	v_mfma_f32_16x16x32_bf16 v[44:47], v[140:143], v[180:183], v[44:47]
	v_mfma_f32_16x16x32_bf16 v[40:43], v[132:135], v[188:191], v[40:43]
	v_mfma_f32_16x16x32_bf16 v[36:39], v[140:143], v[188:191], v[36:39]
	v_mfma_f32_16x16x32_bf16 v[64:67], v[136:139], v[168:171], v[64:67]
	v_mfma_f32_16x16x32_bf16 v[60:63], v[144:147], v[168:171], v[60:63]
	v_mfma_f32_16x16x32_bf16 v[56:59], v[136:139], v[176:179], v[56:59]
	v_mfma_f32_16x16x32_bf16 v[52:55], v[144:147], v[176:179], v[52:55]
	v_mfma_f32_16x16x32_bf16 v[48:51], v[136:139], v[184:187], v[48:51]
	v_mfma_f32_16x16x32_bf16 v[44:47], v[144:147], v[184:187], v[44:47]
	v_mfma_f32_16x16x32_bf16 v[40:43], v[136:139], v[192:195], v[40:43]
	v_mfma_f32_16x16x32_bf16 v[36:39], v[144:147], v[192:195], v[36:39]
	v_mfma_f32_16x16x32_bf16 v[32:35], v[148:151], v[164:167], v[32:35]
	v_mfma_f32_16x16x32_bf16 v[28:31], v[156:159], v[164:167], v[28:31]
	v_mfma_f32_16x16x32_bf16 v[24:27], v[148:151], v[172:175], v[24:27]
	v_mfma_f32_16x16x32_bf16 v[20:23], v[156:159], v[172:175], v[20:23]
	v_mfma_f32_16x16x32_bf16 v[16:19], v[148:151], v[180:183], v[16:19]
	v_mfma_f32_16x16x32_bf16 v[12:15], v[156:159], v[180:183], v[12:15]
	v_mfma_f32_16x16x32_bf16 v[6:9], v[148:151], v[188:191], v[8:11]
	v_mfma_f32_16x16x32_bf16 v[2:5], v[156:159], v[188:191], v[2:5]
	v_mfma_f32_16x16x32_bf16 v[32:35], v[152:155], v[168:171], v[32:35]
	v_mfma_f32_16x16x32_bf16 v[28:31], v[160:163], v[168:171], v[28:31]
	v_mfma_f32_16x16x32_bf16 v[24:27], v[152:155], v[176:179], v[24:27]
	v_mfma_f32_16x16x32_bf16 v[20:23], v[160:163], v[176:179], v[20:23]
	v_mfma_f32_16x16x32_bf16 v[16:19], v[152:155], v[184:187], v[16:19]
	v_mfma_f32_16x16x32_bf16 v[12:15], v[160:163], v[184:187], v[12:15]
	v_mfma_f32_16x16x32_bf16 v[8:11], v[152:155], v[192:195], v[6:9]
	v_mfma_f32_16x16x32_bf16 v[4:7], v[160:163], v[192:195], v[2:5]
	s_barrier
	s_add_i32 s57, s57, 2
	s_add_u32 s30, s30, 0x100
	s_addc_u32 s31, s31, 0
	s_add_u32 s55, s55, 0x100
	s_addc_u32 s56, s56, 0
	s_cmp_gt_u32 s57, 29
	s_cbranch_scc0 .LBB0_577
	s_and_b64 vcc, exec, s[20:21]
	s_cbranch_vccz .LBB0_580
	s_barrier

.LBB0_779:
	s_add_u32 s34, s30, 0xfff80080
	s_addc_u32 s35, s31, -1
	s_add_i32 s66, 0, 0x10000
	s_cmp_eq_u32 s57, 28
	s_cselect_b32 s43, s25, s35
	s_cselect_b32 s42, s53, s34
	s_cselect_b32 s35, s23, s56
	s_cselect_b32 s34, s54, s55
	s_add_i32 s73, 0, 0x14000
	v_add_u32_e32 v114, s66, v157
	v_add_u32_e32 v156, s73, v157
	ds_read_b128 v[90:93], v114
	ds_read_b128 v[94:97], v114 offset:1024
	ds_read_b128 v[106:109], v114 offset:2048
	ds_read_b128 v[114:117], v114 offset:3072
	ds_read_b128 v[162:165], v156
	ds_read_b128 v[166:169], v156 offset:1024
	ds_read_b128 v[170:173], v156 offset:2048
	ds_read_b128 v[174:177], v156 offset:3072
	v_lshl_add_u64 v[158:159], s[30:31], 0, v[152:153]
	s_add_i32 m0, s14, 0xc000
	ds_read_b128 v[178:181], v161
	ds_read_b128 v[182:185], v161 offset:1024
	ds_read_b128 v[186:189], v161 offset:2048
	ds_read_b128 v[190:193], v161 offset:3072
	ds_read_b128 v[200:203], v161 offset:4096
	ds_read_b128 v[204:207], v161 offset:5120
	ds_read_b128 v[208:211], v161 offset:6144
	ds_read_b128 v[212:215], v161 offset:7168
	global_load_lds_dwordx4 v[158:159], off
	v_lshl_add_u64 v[158:159], s[30:31], 0, v[154:155]
	s_add_i32 m0, s14, 0xe000
	s_nop 0
	global_load_lds_dwordx4 v[158:159], off
	s_waitcnt vmcnt(8)
	s_waitcnt lgkmcnt(0)
	s_barrier
	s_waitcnt lgkmcnt(0)
	v_mfma_i32_16x16x64_i8 v[142:145], v[90:93], v[178:181], v[142:145]
	v_mfma_i32_16x16x64_i8 v[138:141], v[106:109], v[178:181], v[138:141]
	v_mfma_i32_16x16x64_i8 v[126:129], v[90:93], v[186:189], v[126:129]
	v_mfma_i32_16x16x64_i8 v[122:125], v[106:109], v[186:189], v[122:125]
	v_mfma_i32_16x16x64_i8 v[102:105], v[90:93], v[200:203], v[102:105]
	v_mfma_i32_16x16x64_i8 v[98:101], v[106:109], v[200:203], v[98:101]
	v_mfma_i32_16x16x64_i8 v[78:81], v[90:93], v[208:211], v[78:81]
	v_mfma_i32_16x16x64_i8 v[74:77], v[106:109], v[208:211], v[74:77]
	v_mfma_i32_16x16x64_i8 v[142:145], v[94:97], v[182:185], v[142:145]
	v_mfma_i32_16x16x64_i8 v[138:141], v[114:117], v[182:185], v[138:141]
	v_mfma_i32_16x16x64_i8 v[126:129], v[94:97], v[190:193], v[126:129]
	v_mfma_i32_16x16x64_i8 v[122:125], v[114:117], v[190:193], v[122:125]
	v_mfma_i32_16x16x64_i8 v[102:105], v[94:97], v[204:207], v[102:105]
	v_mfma_i32_16x16x64_i8 v[98:101], v[114:117], v[204:207], v[98:101]
	v_mfma_i32_16x16x64_i8 v[78:81], v[94:97], v[212:215], v[78:81]
	v_mfma_i32_16x16x64_i8 v[74:77], v[114:117], v[212:215], v[74:77]
	v_mfma_i32_16x16x64_i8 v[134:137], v[162:165], v[178:181], v[134:137]
	v_mfma_i32_16x16x64_i8 v[130:133], v[170:173], v[178:181], v[130:133]
	v_mfma_i32_16x16x64_i8 v[118:121], v[162:165], v[186:189], v[118:121]
	v_mfma_i32_16x16x64_i8 v[110:113], v[170:173], v[186:189], v[110:113]
	v_mfma_i32_16x16x64_i8 v[86:89], v[162:165], v[200:203], v[86:89]
	v_mfma_i32_16x16x64_i8 v[82:85], v[170:173], v[200:203], v[82:85]
	v_mfma_i32_16x16x64_i8 v[70:73], v[162:165], v[208:211], v[70:73]
	v_mfma_i32_16x16x64_i8 v[66:69], v[170:173], v[208:211], v[66:69]
	v_mfma_i32_16x16x64_i8 v[134:137], v[166:169], v[182:185], v[134:137]
	v_mfma_i32_16x16x64_i8 v[130:133], v[174:177], v[182:185], v[130:133]
	v_mfma_i32_16x16x64_i8 v[118:121], v[166:169], v[190:193], v[118:121]
	v_mfma_i32_16x16x64_i8 v[110:113], v[174:177], v[190:193], v[110:113]
	v_mfma_i32_16x16x64_i8 v[86:89], v[166:169], v[204:207], v[86:89]
	v_mfma_i32_16x16x64_i8 v[82:85], v[174:177], v[204:207], v[82:85]
	v_mfma_i32_16x16x64_i8 v[70:73], v[166:169], v[212:215], v[70:73]
	v_mfma_i32_16x16x64_i8 v[66:69], v[174:177], v[212:215], v[66:69]
	s_barrier
	s_add_i32 s66, s66, s9
	v_lshl_add_u64 v[158:159], s[34:35], 0, v[0:1]
	s_mov_b32 m0, s66
	ds_read_b128 v[178:181], v161 offset:16384
	ds_read_b128 v[182:185], v161 offset:17408
	ds_read_b128 v[186:189], v161 offset:18432
	ds_read_b128 v[190:193], v161 offset:19456
	ds_read_b128 v[200:203], v161 offset:20480
	ds_read_b128 v[204:207], v161 offset:21504
	ds_read_b128 v[208:211], v161 offset:22528
	ds_read_b128 v[212:215], v161 offset:23552
	global_load_lds_dwordx4 v[158:159], off
	s_add_i32 m0, s66, 0x2000
	s_add_u32 s66, s34, 0x80000
	v_lshl_add_u64 v[194:195], s[34:35], 0, v[146:147]
	s_addc_u32 s67, s35, 0
	s_add_i32 s73, s73, s9
	global_load_lds_dwordx4 v[194:195], off
	v_lshl_add_u64 v[216:217], s[66:67], 0, v[0:1]
	s_mov_b32 m0, s73
	v_lshl_add_u64 v[218:219], s[42:43], 0, v[148:149]
	global_load_lds_dwordx4 v[216:217], off
	v_lshl_add_u64 v[216:217], s[66:67], 0, v[146:147]
	s_add_i32 m0, s73, 0x2000
	s_nop 0
	global_load_lds_dwordx4 v[216:217], off
	v_lshl_add_u64 v[216:217], s[42:43], 0, v[150:151]
	s_mov_b32 m0, s14
	s_nop 0
	global_load_lds_dwordx4 v[216:217], off
	s_mov_b32 m0, s15
	s_nop 0
	global_load_lds_dwordx4 v[218:219], off
	s_waitcnt vmcnt(8)
	s_waitcnt lgkmcnt(0)
	s_barrier
	s_waitcnt lgkmcnt(0)
	v_mfma_i32_16x16x64_i8 v[62:65], v[90:93], v[178:181], v[62:65]
	v_mfma_i32_16x16x64_i8 v[58:61], v[106:109], v[178:181], v[58:61]
	v_mfma_i32_16x16x64_i8 v[46:49], v[90:93], v[186:189], v[46:49]
	v_mfma_i32_16x16x64_i8 v[42:45], v[106:109], v[186:189], v[42:45]
	v_mfma_i32_16x16x64_i8 v[30:33], v[90:93], v[200:203], v[30:33]
	v_mfma_i32_16x16x64_i8 v[26:29], v[106:109], v[200:203], v[26:29]
	v_mfma_i32_16x16x64_i8 v[14:17], v[90:93], v[208:211], v[14:17]
	v_mfma_i32_16x16x64_i8 v[10:13], v[106:109], v[208:211], v[10:13]
	v_mfma_i32_16x16x64_i8 v[62:65], v[94:97], v[182:185], v[62:65]
	v_mfma_i32_16x16x64_i8 v[58:61], v[114:117], v[182:185], v[58:61]
	v_mfma_i32_16x16x64_i8 v[46:49], v[94:97], v[190:193], v[46:49]
	v_mfma_i32_16x16x64_i8 v[42:45], v[114:117], v[190:193], v[42:45]
	v_mfma_i32_16x16x64_i8 v[30:33], v[94:97], v[204:207], v[30:33]
	v_mfma_i32_16x16x64_i8 v[26:29], v[114:117], v[204:207], v[26:29]
	v_mfma_i32_16x16x64_i8 v[14:17], v[94:97], v[212:215], v[14:17]
	v_mfma_i32_16x16x64_i8 v[10:13], v[114:117], v[212:215], v[10:13]
	v_mfma_i32_16x16x64_i8 v[54:57], v[162:165], v[178:181], v[54:57]
	v_mfma_i32_16x16x64_i8 v[50:53], v[170:173], v[178:181], v[50:53]
	v_mfma_i32_16x16x64_i8 v[38:41], v[162:165], v[186:189], v[38:41]
	v_mfma_i32_16x16x64_i8 v[34:37], v[170:173], v[186:189], v[34:37]
	v_mfma_i32_16x16x64_i8 v[22:25], v[162:165], v[200:203], v[22:25]
	v_mfma_i32_16x16x64_i8 v[18:21], v[170:173], v[200:203], v[18:21]
	v_mfma_i32_16x16x64_i8 v[6:9], v[162:165], v[208:211], v[6:9]
	v_mfma_i32_16x16x64_i8 v[2:5], v[170:173], v[208:211], v[2:5]
	v_mfma_i32_16x16x64_i8 v[54:57], v[166:169], v[182:185], v[54:57]
	v_mfma_i32_16x16x64_i8 v[50:53], v[174:177], v[182:185], v[50:53]
	v_mfma_i32_16x16x64_i8 v[38:41], v[166:169], v[190:193], v[38:41]
	v_mfma_i32_16x16x64_i8 v[34:37], v[174:177], v[190:193], v[34:37]
	v_mfma_i32_16x16x64_i8 v[22:25], v[166:169], v[204:207], v[22:25]
	v_mfma_i32_16x16x64_i8 v[18:21], v[174:177], v[204:207], v[18:21]
	v_mfma_i32_16x16x64_i8 v[6:9], v[166:169], v[212:215], v[6:9]
	v_mfma_i32_16x16x64_i8 v[2:5], v[174:177], v[212:215], v[2:5]
	s_barrier
	s_add_i32 s66, 0, 0x18000
	s_add_i32 s67, 0, 0x1c000
	v_add_u32_e32 v114, s66, v157
	v_add_u32_e32 v156, s67, v157
	ds_read_b128 v[90:93], v114
	ds_read_b128 v[94:97], v114 offset:1024
	ds_read_b128 v[106:109], v114 offset:2048
	ds_read_b128 v[114:117], v114 offset:3072
	ds_read_b128 v[162:165], v156
	ds_read_b128 v[166:169], v156 offset:1024
	ds_read_b128 v[170:173], v156 offset:2048
	ds_read_b128 v[174:177], v156 offset:3072
	s_add_u32 s42, s42, 0x80000
	s_addc_u32 s43, s43, 0
	s_mov_b32 m0, s46
	v_lshl_add_u64 v[220:221], s[42:43], 0, v[150:151]
	ds_read_b128 v[178:181], v161 offset:32768
	ds_read_b128 v[182:185], v161 offset:33792
	ds_read_b128 v[186:189], v161 offset:34816
	ds_read_b128 v[190:193], v161 offset:35840
	ds_read_b128 v[200:203], v161 offset:36864
	ds_read_b128 v[204:207], v161 offset:37888
	ds_read_b128 v[208:211], v161 offset:38912
	ds_read_b128 v[212:215], v161 offset:39936
	global_load_lds_dwordx4 v[220:221], off
	v_lshl_add_u64 v[220:221], s[42:43], 0, v[148:149]
	s_mov_b32 m0, s47
	s_nop 0
	global_load_lds_dwordx4 v[220:221], off
	s_waitcnt vmcnt(8)
	s_waitcnt lgkmcnt(0)
	s_barrier
	s_waitcnt lgkmcnt(0)
	v_mfma_i32_16x16x64_i8 v[142:145], v[90:93], v[178:181], v[142:145]
	v_mfma_i32_16x16x64_i8 v[138:141], v[106:109], v[178:181], v[138:141]
	v_mfma_i32_16x16x64_i8 v[126:129], v[90:93], v[186:189], v[126:129]
	v_mfma_i32_16x16x64_i8 v[122:125], v[106:109], v[186:189], v[122:125]
	v_mfma_i32_16x16x64_i8 v[102:105], v[90:93], v[200:203], v[102:105]
	v_mfma_i32_16x16x64_i8 v[98:101], v[106:109], v[200:203], v[98:101]
	v_mfma_i32_16x16x64_i8 v[78:81], v[90:93], v[208:211], v[78:81]
	v_mfma_i32_16x16x64_i8 v[74:77], v[106:109], v[208:211], v[74:77]
	v_mfma_i32_16x16x64_i8 v[142:145], v[94:97], v[182:185], v[142:145]
	v_mfma_i32_16x16x64_i8 v[138:141], v[114:117], v[182:185], v[138:141]
	v_mfma_i32_16x16x64_i8 v[126:129], v[94:97], v[190:193], v[126:129]
	v_mfma_i32_16x16x64_i8 v[122:125], v[114:117], v[190:193], v[122:125]
	v_mfma_i32_16x16x64_i8 v[102:105], v[94:97], v[204:207], v[102:105]
	v_mfma_i32_16x16x64_i8 v[98:101], v[114:117], v[204:207], v[98:101]
	v_mfma_i32_16x16x64_i8 v[78:81], v[94:97], v[212:215], v[78:81]
	v_mfma_i32_16x16x64_i8 v[74:77], v[114:117], v[212:215], v[74:77]
	v_mfma_i32_16x16x64_i8 v[134:137], v[162:165], v[178:181], v[134:137]
	v_mfma_i32_16x16x64_i8 v[130:133], v[170:173], v[178:181], v[130:133]
	v_mfma_i32_16x16x64_i8 v[118:121], v[162:165], v[186:189], v[118:121]
	v_mfma_i32_16x16x64_i8 v[110:113], v[170:173], v[186:189], v[110:113]
	v_mfma_i32_16x16x64_i8 v[86:89], v[162:165], v[200:203], v[86:89]
	v_mfma_i32_16x16x64_i8 v[82:85], v[170:173], v[200:203], v[82:85]
	v_mfma_i32_16x16x64_i8 v[70:73], v[162:165], v[208:211], v[70:73]
	v_mfma_i32_16x16x64_i8 v[66:69], v[170:173], v[208:211], v[66:69]
	v_mfma_i32_16x16x64_i8 v[134:137], v[166:169], v[182:185], v[134:137]
	v_mfma_i32_16x16x64_i8 v[130:133], v[174:177], v[182:185], v[130:133]
	v_mfma_i32_16x16x64_i8 v[118:121], v[166:169], v[190:193], v[118:121]
	v_mfma_i32_16x16x64_i8 v[110:113], v[174:177], v[190:193], v[110:113]
	v_mfma_i32_16x16x64_i8 v[86:89], v[166:169], v[204:207], v[86:89]
	v_mfma_i32_16x16x64_i8 v[82:85], v[174:177], v[204:207], v[82:85]
	v_mfma_i32_16x16x64_i8 v[70:73], v[166:169], v[212:215], v[70:73]
	v_mfma_i32_16x16x64_i8 v[66:69], v[174:177], v[212:215], v[66:69]
	s_barrier
	s_add_i32 s42, s66, s9
	v_lshl_add_u64 v[158:159], v[158:159], 0, s[12:13]
	s_mov_b32 m0, s42
	ds_read_b128 v[178:181], v161 offset:49152
	ds_read_b128 v[182:185], v161 offset:50176
	ds_read_b128 v[186:189], v161 offset:51200
	ds_read_b128 v[190:193], v161 offset:52224
	ds_read_b128 v[200:203], v161 offset:53248
	ds_read_b128 v[204:207], v161 offset:54272
	ds_read_b128 v[208:211], v161 offset:55296
	ds_read_b128 v[212:215], v161 offset:56320
	global_load_lds_dwordx4 v[158:159], off
	s_add_i32 m0, s42, 0x2000
	s_add_u32 s34, s34, 0x80080
	v_lshl_add_u64 v[158:159], v[194:195], 0, s[12:13]
	s_addc_u32 s35, s35, 0
	s_add_i32 s42, s67, s9
	global_load_lds_dwordx4 v[158:159], off
	v_lshl_add_u64 v[158:159], s[34:35], 0, v[0:1]
	s_mov_b32 m0, s42
	s_nop 0
	global_load_lds_dwordx4 v[158:159], off
	v_lshl_add_u64 v[158:159], s[34:35], 0, v[146:147]
	s_add_i32 m0, s42, 0x2000
	s_nop 0
	global_load_lds_dwordx4 v[158:159], off
	v_lshl_add_u64 v[158:159], v[216:217], 0, s[12:13]
	s_mov_b32 m0, s50
	s_nop 0
	global_load_lds_dwordx4 v[158:159], off
	v_lshl_add_u64 v[158:159], v[218:219], 0, s[12:13]
	s_mov_b32 m0, s51
	s_nop 0
	global_load_lds_dwordx4 v[158:159], off
	s_waitcnt vmcnt(8)
	s_waitcnt lgkmcnt(0)
	s_barrier
	s_waitcnt lgkmcnt(0)
	v_mfma_i32_16x16x64_i8 v[62:65], v[90:93], v[178:181], v[62:65]
	v_mfma_i32_16x16x64_i8 v[58:61], v[106:109], v[178:181], v[58:61]
	v_mfma_i32_16x16x64_i8 v[46:49], v[90:93], v[186:189], v[46:49]
	v_mfma_i32_16x16x64_i8 v[42:45], v[106:109], v[186:189], v[42:45]
	v_mfma_i32_16x16x64_i8 v[30:33], v[90:93], v[200:203], v[30:33]
	v_mfma_i32_16x16x64_i8 v[26:29], v[106:109], v[200:203], v[26:29]
	v_mfma_i32_16x16x64_i8 v[14:17], v[90:93], v[208:211], v[14:17]
	v_mfma_i32_16x16x64_i8 v[10:13], v[106:109], v[208:211], v[10:13]
	v_mfma_i32_16x16x64_i8 v[62:65], v[94:97], v[182:185], v[62:65]
	v_mfma_i32_16x16x64_i8 v[58:61], v[114:117], v[182:185], v[58:61]
	v_mfma_i32_16x16x64_i8 v[46:49], v[94:97], v[190:193], v[46:49]
	v_mfma_i32_16x16x64_i8 v[42:45], v[114:117], v[190:193], v[42:45]
	v_mfma_i32_16x16x64_i8 v[30:33], v[94:97], v[204:207], v[30:33]
	v_mfma_i32_16x16x64_i8 v[26:29], v[114:117], v[204:207], v[26:29]
	v_mfma_i32_16x16x64_i8 v[14:17], v[94:97], v[212:215], v[14:17]
	v_mfma_i32_16x16x64_i8 v[10:13], v[114:117], v[212:215], v[10:13]
	v_mfma_i32_16x16x64_i8 v[54:57], v[162:165], v[178:181], v[54:57]
	v_mfma_i32_16x16x64_i8 v[50:53], v[170:173], v[178:181], v[50:53]
	v_mfma_i32_16x16x64_i8 v[38:41], v[162:165], v[186:189], v[38:41]
	v_mfma_i32_16x16x64_i8 v[34:37], v[170:173], v[186:189], v[34:37]
	v_mfma_i32_16x16x64_i8 v[22:25], v[162:165], v[200:203], v[22:25]
	v_mfma_i32_16x16x64_i8 v[18:21], v[170:173], v[200:203], v[18:21]
	v_mfma_i32_16x16x64_i8 v[6:9], v[162:165], v[208:211], v[6:9]
	v_mfma_i32_16x16x64_i8 v[2:5], v[170:173], v[208:211], v[2:5]
	v_mfma_i32_16x16x64_i8 v[54:57], v[166:169], v[182:185], v[54:57]
	v_mfma_i32_16x16x64_i8 v[50:53], v[174:177], v[182:185], v[50:53]
	v_mfma_i32_16x16x64_i8 v[38:41], v[166:169], v[190:193], v[38:41]
	v_mfma_i32_16x16x64_i8 v[34:37], v[174:177], v[190:193], v[34:37]
	v_mfma_i32_16x16x64_i8 v[22:25], v[166:169], v[204:207], v[22:25]
	v_mfma_i32_16x16x64_i8 v[18:21], v[174:177], v[204:207], v[18:21]
	v_mfma_i32_16x16x64_i8 v[6:9], v[166:169], v[212:215], v[6:9]
	v_mfma_i32_16x16x64_i8 v[2:5], v[174:177], v[212:215], v[2:5]
	s_barrier
	s_add_i32 s57, s57, 2
	s_add_u32 s30, s30, 0x100
	s_addc_u32 s31, s31, 0
	s_add_u32 s55, s55, 0x100
	s_addc_u32 s56, s56, 0
	s_cmp_gt_u32 s57, 29
	s_cbranch_scc0 .LBB0_779
	s_and_b64 vcc, exec, s[20:21]
	s_mov_b32 s54, 0x5c401000
	s_cbranch_vccz .LBB0_782
	s_barrier

.LBB0_801:
	s_add_u32 s34, s30, 0xfff00080
	s_addc_u32 s35, s31, -1
	s_add_i32 s54, 0, 0x10000
	s_cmp_eq_u32 s53, 60
	s_cselect_b32 s41, s25, s35
	s_cselect_b32 s40, s49, s34
	s_cselect_b32 s35, s23, s52
	s_cselect_b32 s34, s50, s51
	s_add_i32 s56, 0, 0x14000
	v_add_u32_e32 v156, s54, v141
	v_add_u32_e32 v172, s56, v141
	ds_read_b128 v[144:147], v156
	ds_read_b128 v[148:151], v156 offset:1024
	ds_read_b128 v[152:155], v156 offset:2048
	ds_read_b128 v[156:159], v156 offset:3072
	ds_read_b128 v[160:163], v172
	ds_read_b128 v[164:167], v172 offset:1024
	ds_read_b128 v[168:171], v172 offset:2048
	ds_read_b128 v[172:175], v172 offset:3072
	v_lshl_add_u64 v[212:213], s[30:31], 0, v[136:137]
	s_add_i32 m0, s14, 0xc000
	ds_read_b128 v[176:179], v143
	ds_read_b128 v[180:183], v143 offset:1024
	ds_read_b128 v[184:187], v143 offset:2048
	ds_read_b128 v[188:191], v143 offset:3072
	ds_read_b128 v[192:195], v143 offset:4096
	ds_read_b128 v[200:203], v143 offset:5120
	ds_read_b128 v[204:207], v143 offset:6144
	ds_read_b128 v[208:211], v143 offset:7168
	global_load_lds_dwordx4 v[212:213], off
	v_lshl_add_u64 v[212:213], s[30:31], 0, v[138:139]
	s_add_i32 m0, s14, 0xe000
	s_nop 0
	global_load_lds_dwordx4 v[212:213], off
	s_waitcnt vmcnt(8)
	s_waitcnt lgkmcnt(0)
	s_barrier
	s_waitcnt lgkmcnt(0)
	v_mfma_f32_16x16x32_bf16 v[126:129], v[144:147], v[176:179], v[126:129]
	v_mfma_f32_16x16x32_bf16 v[122:125], v[152:155], v[176:179], v[122:125]
	v_mfma_f32_16x16x32_bf16 v[118:121], v[144:147], v[184:187], v[118:121]
	v_mfma_f32_16x16x32_bf16 v[114:117], v[152:155], v[184:187], v[114:117]
	v_mfma_f32_16x16x32_bf16 v[102:105], v[144:147], v[192:195], v[102:105]
	v_mfma_f32_16x16x32_bf16 v[98:101], v[152:155], v[192:195], v[98:101]
	v_mfma_f32_16x16x32_bf16 v[86:89], v[144:147], v[204:207], v[86:89]
	v_mfma_f32_16x16x32_bf16 v[82:85], v[152:155], v[204:207], v[82:85]
	v_mfma_f32_16x16x32_bf16 v[126:129], v[148:151], v[180:183], v[126:129]
	v_mfma_f32_16x16x32_bf16 v[122:125], v[156:159], v[180:183], v[122:125]
	v_mfma_f32_16x16x32_bf16 v[118:121], v[148:151], v[188:191], v[118:121]
	v_mfma_f32_16x16x32_bf16 v[114:117], v[156:159], v[188:191], v[114:117]
	v_mfma_f32_16x16x32_bf16 v[102:105], v[148:151], v[200:203], v[102:105]
	v_mfma_f32_16x16x32_bf16 v[98:101], v[156:159], v[200:203], v[98:101]
	v_mfma_f32_16x16x32_bf16 v[86:89], v[148:151], v[208:211], v[86:89]
	v_mfma_f32_16x16x32_bf16 v[82:85], v[156:159], v[208:211], v[82:85]
	v_mfma_f32_16x16x32_bf16 v[110:113], v[160:163], v[176:179], v[110:113]
	v_mfma_f32_16x16x32_bf16 v[106:109], v[168:171], v[176:179], v[106:109]
	v_mfma_f32_16x16x32_bf16 v[94:97], v[160:163], v[184:187], v[94:97]
	v_mfma_f32_16x16x32_bf16 v[90:93], v[168:171], v[184:187], v[90:93]
	v_mfma_f32_16x16x32_bf16 v[78:81], v[160:163], v[192:195], v[78:81]
	v_mfma_f32_16x16x32_bf16 v[74:77], v[168:171], v[192:195], v[74:77]
	v_mfma_f32_16x16x32_bf16 v[70:73], v[160:163], v[204:207], v[70:73]
	v_mfma_f32_16x16x32_bf16 v[66:69], v[168:171], v[204:207], v[66:69]
	v_mfma_f32_16x16x32_bf16 v[110:113], v[164:167], v[180:183], v[110:113]
	v_mfma_f32_16x16x32_bf16 v[106:109], v[172:175], v[180:183], v[106:109]
	v_mfma_f32_16x16x32_bf16 v[94:97], v[164:167], v[188:191], v[94:97]
	v_mfma_f32_16x16x32_bf16 v[90:93], v[172:175], v[188:191], v[90:93]
	v_mfma_f32_16x16x32_bf16 v[78:81], v[164:167], v[200:203], v[78:81]
	v_mfma_f32_16x16x32_bf16 v[74:77], v[172:175], v[200:203], v[74:77]
	v_mfma_f32_16x16x32_bf16 v[70:73], v[164:167], v[208:211], v[70:73]
	v_mfma_f32_16x16x32_bf16 v[66:69], v[172:175], v[208:211], v[66:69]
	s_barrier
	s_add_i32 s54, s54, s9
	v_lshl_add_u64 v[212:213], s[34:35], 0, v[0:1]
	s_mov_b32 m0, s54
	ds_read_b128 v[176:179], v143 offset:16384
	ds_read_b128 v[180:183], v143 offset:17408
	ds_read_b128 v[184:187], v143 offset:18432
	ds_read_b128 v[188:191], v143 offset:19456
	ds_read_b128 v[192:195], v143 offset:20480
	ds_read_b128 v[200:203], v143 offset:21504
	ds_read_b128 v[204:207], v143 offset:22528
	ds_read_b128 v[208:211], v143 offset:23552
	global_load_lds_dwordx4 v[212:213], off
	s_add_i32 m0, s54, 0x2000
	s_add_u32 s54, s34, 0x100000
	v_lshl_add_u64 v[214:215], s[34:35], 0, v[130:131]
	s_addc_u32 s55, s35, 0
	s_add_i32 s56, s56, s9
	global_load_lds_dwordx4 v[214:215], off
	v_lshl_add_u64 v[216:217], s[54:55], 0, v[0:1]
	s_mov_b32 m0, s56
	v_lshl_add_u64 v[218:219], s[40:41], 0, v[132:133]
	global_load_lds_dwordx4 v[216:217], off
	v_lshl_add_u64 v[216:217], s[54:55], 0, v[130:131]
	s_add_i32 m0, s56, 0x2000
	s_nop 0
	global_load_lds_dwordx4 v[216:217], off
	v_lshl_add_u64 v[216:217], s[40:41], 0, v[134:135]
	s_mov_b32 m0, s14
	s_nop 0
	global_load_lds_dwordx4 v[216:217], off
	s_mov_b32 m0, s15
	s_nop 0
	global_load_lds_dwordx4 v[218:219], off
	s_waitcnt vmcnt(8)
	s_waitcnt lgkmcnt(0)
	s_barrier
	s_waitcnt lgkmcnt(0)
	v_mfma_f32_16x16x32_bf16 v[62:65], v[144:147], v[176:179], v[62:65]
	v_mfma_f32_16x16x32_bf16 v[58:61], v[152:155], v[176:179], v[58:61]
	v_mfma_f32_16x16x32_bf16 v[54:57], v[144:147], v[184:187], v[54:57]
	v_mfma_f32_16x16x32_bf16 v[50:53], v[152:155], v[184:187], v[50:53]
	v_mfma_f32_16x16x32_bf16 v[38:41], v[144:147], v[192:195], v[38:41]
	v_mfma_f32_16x16x32_bf16 v[34:37], v[152:155], v[192:195], v[34:37]
	v_mfma_f32_16x16x32_bf16 v[22:25], v[144:147], v[204:207], v[22:25]
	v_mfma_f32_16x16x32_bf16 v[18:21], v[152:155], v[204:207], v[18:21]
	v_mfma_f32_16x16x32_bf16 v[62:65], v[148:151], v[180:183], v[62:65]
	v_mfma_f32_16x16x32_bf16 v[58:61], v[156:159], v[180:183], v[58:61]
	v_mfma_f32_16x16x32_bf16 v[54:57], v[148:151], v[188:191], v[54:57]
	v_mfma_f32_16x16x32_bf16 v[50:53], v[156:159], v[188:191], v[50:53]
	v_mfma_f32_16x16x32_bf16 v[38:41], v[148:151], v[200:203], v[38:41]
	v_mfma_f32_16x16x32_bf16 v[34:37], v[156:159], v[200:203], v[34:37]
	v_mfma_f32_16x16x32_bf16 v[22:25], v[148:151], v[208:211], v[22:25]
	v_mfma_f32_16x16x32_bf16 v[18:21], v[156:159], v[208:211], v[18:21]
	v_mfma_f32_16x16x32_bf16 v[46:49], v[160:163], v[176:179], v[46:49]
	v_mfma_f32_16x16x32_bf16 v[42:45], v[168:171], v[176:179], v[42:45]
	v_mfma_f32_16x16x32_bf16 v[30:33], v[160:163], v[184:187], v[30:33]
	v_mfma_f32_16x16x32_bf16 v[26:29], v[168:171], v[184:187], v[26:29]
	v_mfma_f32_16x16x32_bf16 v[14:17], v[160:163], v[192:195], v[14:17]
	v_mfma_f32_16x16x32_bf16 v[10:13], v[168:171], v[192:195], v[10:13]
	v_mfma_f32_16x16x32_bf16 v[6:9], v[160:163], v[204:207], v[6:9]
	v_mfma_f32_16x16x32_bf16 v[2:5], v[168:171], v[204:207], v[2:5]
	v_mfma_f32_16x16x32_bf16 v[46:49], v[164:167], v[180:183], v[46:49]
	v_mfma_f32_16x16x32_bf16 v[42:45], v[172:175], v[180:183], v[42:45]
	v_mfma_f32_16x16x32_bf16 v[30:33], v[164:167], v[188:191], v[30:33]
	v_mfma_f32_16x16x32_bf16 v[26:29], v[172:175], v[188:191], v[26:29]
	v_mfma_f32_16x16x32_bf16 v[14:17], v[164:167], v[200:203], v[14:17]
	v_mfma_f32_16x16x32_bf16 v[10:13], v[172:175], v[200:203], v[10:13]
	v_mfma_f32_16x16x32_bf16 v[6:9], v[164:167], v[208:211], v[6:9]
	v_mfma_f32_16x16x32_bf16 v[2:5], v[172:175], v[208:211], v[2:5]
	s_barrier
	s_add_i32 s54, 0, 0x18000
	s_add_i32 s55, 0, 0x1c000
	v_add_u32_e32 v156, s54, v141
	v_add_u32_e32 v172, s55, v141
	ds_read_b128 v[144:147], v156
	ds_read_b128 v[148:151], v156 offset:1024
	ds_read_b128 v[152:155], v156 offset:2048
	ds_read_b128 v[156:159], v156 offset:3072
	ds_read_b128 v[160:163], v172
	ds_read_b128 v[164:167], v172 offset:1024
	ds_read_b128 v[168:171], v172 offset:2048
	ds_read_b128 v[172:175], v172 offset:3072
	s_add_u32 s40, s40, 0x100000
	s_addc_u32 s41, s41, 0
	s_mov_b32 m0, s18
	v_lshl_add_u64 v[220:221], s[40:41], 0, v[134:135]
	ds_read_b128 v[176:179], v143 offset:32768
	ds_read_b128 v[180:183], v143 offset:33792
	ds_read_b128 v[184:187], v143 offset:34816
	ds_read_b128 v[188:191], v143 offset:35840
	ds_read_b128 v[192:195], v143 offset:36864
	ds_read_b128 v[200:203], v143 offset:37888
	ds_read_b128 v[204:207], v143 offset:38912
	ds_read_b128 v[208:211], v143 offset:39936
	global_load_lds_dwordx4 v[220:221], off
	v_lshl_add_u64 v[220:221], s[40:41], 0, v[132:133]
	s_mov_b32 m0, s19
	s_nop 0
	global_load_lds_dwordx4 v[220:221], off
	s_waitcnt vmcnt(8)
	s_waitcnt lgkmcnt(0)
	s_barrier
	s_waitcnt lgkmcnt(0)
	v_mfma_f32_16x16x32_bf16 v[126:129], v[144:147], v[176:179], v[126:129]
	v_mfma_f32_16x16x32_bf16 v[122:125], v[152:155], v[176:179], v[122:125]
	v_mfma_f32_16x16x32_bf16 v[118:121], v[144:147], v[184:187], v[118:121]
	v_mfma_f32_16x16x32_bf16 v[114:117], v[152:155], v[184:187], v[114:117]
	v_mfma_f32_16x16x32_bf16 v[102:105], v[144:147], v[192:195], v[102:105]
	v_mfma_f32_16x16x32_bf16 v[98:101], v[152:155], v[192:195], v[98:101]
	v_mfma_f32_16x16x32_bf16 v[86:89], v[144:147], v[204:207], v[86:89]
	v_mfma_f32_16x16x32_bf16 v[82:85], v[152:155], v[204:207], v[82:85]
	v_mfma_f32_16x16x32_bf16 v[126:129], v[148:151], v[180:183], v[126:129]
	v_mfma_f32_16x16x32_bf16 v[122:125], v[156:159], v[180:183], v[122:125]
	v_mfma_f32_16x16x32_bf16 v[118:121], v[148:151], v[188:191], v[118:121]
	v_mfma_f32_16x16x32_bf16 v[114:117], v[156:159], v[188:191], v[114:117]
	v_mfma_f32_16x16x32_bf16 v[102:105], v[148:151], v[200:203], v[102:105]
	v_mfma_f32_16x16x32_bf16 v[98:101], v[156:159], v[200:203], v[98:101]
	v_mfma_f32_16x16x32_bf16 v[86:89], v[148:151], v[208:211], v[86:89]
	v_mfma_f32_16x16x32_bf16 v[82:85], v[156:159], v[208:211], v[82:85]
	v_mfma_f32_16x16x32_bf16 v[110:113], v[160:163], v[176:179], v[110:113]
	v_mfma_f32_16x16x32_bf16 v[106:109], v[168:171], v[176:179], v[106:109]
	v_mfma_f32_16x16x32_bf16 v[94:97], v[160:163], v[184:187], v[94:97]
	v_mfma_f32_16x16x32_bf16 v[90:93], v[168:171], v[184:187], v[90:93]
	v_mfma_f32_16x16x32_bf16 v[78:81], v[160:163], v[192:195], v[78:81]
	v_mfma_f32_16x16x32_bf16 v[74:77], v[168:171], v[192:195], v[74:77]
	v_mfma_f32_16x16x32_bf16 v[70:73], v[160:163], v[204:207], v[70:73]
	v_mfma_f32_16x16x32_bf16 v[66:69], v[168:171], v[204:207], v[66:69]
	v_mfma_f32_16x16x32_bf16 v[110:113], v[164:167], v[180:183], v[110:113]
	v_mfma_f32_16x16x32_bf16 v[106:109], v[172:175], v[180:183], v[106:109]
	v_mfma_f32_16x16x32_bf16 v[94:97], v[164:167], v[188:191], v[94:97]
	v_mfma_f32_16x16x32_bf16 v[90:93], v[172:175], v[188:191], v[90:93]
	v_mfma_f32_16x16x32_bf16 v[78:81], v[164:167], v[200:203], v[78:81]
	v_mfma_f32_16x16x32_bf16 v[74:77], v[172:175], v[200:203], v[74:77]
	v_mfma_f32_16x16x32_bf16 v[70:73], v[164:167], v[208:211], v[70:73]
	v_mfma_f32_16x16x32_bf16 v[66:69], v[172:175], v[208:211], v[66:69]
	s_barrier
	s_add_i32 s40, s54, s9
	v_lshl_add_u64 v[212:213], v[212:213], 0, s[12:13]
	s_mov_b32 m0, s40
	ds_read_b128 v[176:179], v143 offset:49152
	ds_read_b128 v[180:183], v143 offset:50176
	ds_read_b128 v[184:187], v143 offset:51200
	ds_read_b128 v[188:191], v143 offset:52224
	ds_read_b128 v[192:195], v143 offset:53248
	ds_read_b128 v[200:203], v143 offset:54272
	ds_read_b128 v[204:207], v143 offset:55296
	ds_read_b128 v[208:211], v143 offset:56320
	global_load_lds_dwordx4 v[212:213], off
	s_add_i32 m0, s40, 0x2000
	s_add_u32 s34, s34, 0x100080
	v_lshl_add_u64 v[212:213], v[214:215], 0, s[12:13]
	s_addc_u32 s35, s35, 0
	s_add_i32 s40, s55, s9
	global_load_lds_dwordx4 v[212:213], off
	v_lshl_add_u64 v[212:213], s[34:35], 0, v[0:1]
	s_mov_b32 m0, s40
	s_nop 0
	global_load_lds_dwordx4 v[212:213], off
	v_lshl_add_u64 v[212:213], s[34:35], 0, v[130:131]
	s_add_i32 m0, s40, 0x2000
	s_nop 0
	global_load_lds_dwordx4 v[212:213], off
	v_lshl_add_u64 v[212:213], v[216:217], 0, s[12:13]
	s_mov_b32 m0, s42
	s_nop 0
	global_load_lds_dwordx4 v[212:213], off
	v_lshl_add_u64 v[212:213], v[218:219], 0, s[12:13]
	s_mov_b32 m0, s43
	s_nop 0
	global_load_lds_dwordx4 v[212:213], off
	s_waitcnt vmcnt(8)
	s_waitcnt lgkmcnt(0)
	s_barrier
	s_waitcnt lgkmcnt(0)
	v_mfma_f32_16x16x32_bf16 v[62:65], v[144:147], v[176:179], v[62:65]
	v_mfma_f32_16x16x32_bf16 v[58:61], v[152:155], v[176:179], v[58:61]
	v_mfma_f32_16x16x32_bf16 v[54:57], v[144:147], v[184:187], v[54:57]
	v_mfma_f32_16x16x32_bf16 v[50:53], v[152:155], v[184:187], v[50:53]
	v_mfma_f32_16x16x32_bf16 v[38:41], v[144:147], v[192:195], v[38:41]
	v_mfma_f32_16x16x32_bf16 v[34:37], v[152:155], v[192:195], v[34:37]
	v_mfma_f32_16x16x32_bf16 v[22:25], v[144:147], v[204:207], v[22:25]
	v_mfma_f32_16x16x32_bf16 v[18:21], v[152:155], v[204:207], v[18:21]
	v_mfma_f32_16x16x32_bf16 v[62:65], v[148:151], v[180:183], v[62:65]
	v_mfma_f32_16x16x32_bf16 v[58:61], v[156:159], v[180:183], v[58:61]
	v_mfma_f32_16x16x32_bf16 v[54:57], v[148:151], v[188:191], v[54:57]
	v_mfma_f32_16x16x32_bf16 v[50:53], v[156:159], v[188:191], v[50:53]
	v_mfma_f32_16x16x32_bf16 v[38:41], v[148:151], v[200:203], v[38:41]
	v_mfma_f32_16x16x32_bf16 v[34:37], v[156:159], v[200:203], v[34:37]
	v_mfma_f32_16x16x32_bf16 v[22:25], v[148:151], v[208:211], v[22:25]
	v_mfma_f32_16x16x32_bf16 v[18:21], v[156:159], v[208:211], v[18:21]
	v_mfma_f32_16x16x32_bf16 v[46:49], v[160:163], v[176:179], v[46:49]
	v_mfma_f32_16x16x32_bf16 v[42:45], v[168:171], v[176:179], v[42:45]
	v_mfma_f32_16x16x32_bf16 v[30:33], v[160:163], v[184:187], v[30:33]
	v_mfma_f32_16x16x32_bf16 v[26:29], v[168:171], v[184:187], v[26:29]
	v_mfma_f32_16x16x32_bf16 v[14:17], v[160:163], v[192:195], v[14:17]
	v_mfma_f32_16x16x32_bf16 v[10:13], v[168:171], v[192:195], v[10:13]
	v_mfma_f32_16x16x32_bf16 v[6:9], v[160:163], v[204:207], v[6:9]
	v_mfma_f32_16x16x32_bf16 v[2:5], v[168:171], v[204:207], v[2:5]
	v_mfma_f32_16x16x32_bf16 v[46:49], v[164:167], v[180:183], v[46:49]
	v_mfma_f32_16x16x32_bf16 v[42:45], v[172:175], v[180:183], v[42:45]
	v_mfma_f32_16x16x32_bf16 v[30:33], v[164:167], v[188:191], v[30:33]
	v_mfma_f32_16x16x32_bf16 v[26:29], v[172:175], v[188:191], v[26:29]
	v_mfma_f32_16x16x32_bf16 v[14:17], v[164:167], v[200:203], v[14:17]
	v_mfma_f32_16x16x32_bf16 v[10:13], v[172:175], v[200:203], v[10:13]
	v_mfma_f32_16x16x32_bf16 v[6:9], v[164:167], v[208:211], v[6:9]
	v_mfma_f32_16x16x32_bf16 v[2:5], v[172:175], v[208:211], v[2:5]
	s_barrier
	s_add_i32 s53, s53, 2
	s_add_u32 s30, s30, 0x100
	s_addc_u32 s31, s31, 0
	s_add_u32 s51, s51, 0x100
	s_addc_u32 s52, s52, 0
	s_cmp_gt_u32 s53, 61
	s_cbranch_scc0 .LBB0_801
	s_and_b64 vcc, exec, s[20:21]
	s_cbranch_vccz .LBB0_804
	s_barrier

	.amdhsa_kernel _Z6mk_fwd4Args
		.amdhsa_group_segment_fixed_size 0
		.amdhsa_private_segment_fixed_size 0
		.amdhsa_kernarg_size 360
		.amdhsa_user_sgpr_count 2
		.amdhsa_user_sgpr_dispatch_ptr 0
		.amdhsa_user_sgpr_queue_ptr 0
		.amdhsa_user_sgpr_kernarg_segment_ptr 1
		.amdhsa_user_sgpr_dispatch_id 0
		.amdhsa_user_sgpr_kernarg_preload_length 0
		.amdhsa_user_sgpr_kernarg_preload_offset 0
		.amdhsa_user_sgpr_private_segment_size 0
		.amdhsa_uses_dynamic_stack 0
		.amdhsa_enable_private_segment 0
		.amdhsa_system_sgpr_workgroup_id_x 1
		.amdhsa_system_sgpr_workgroup_id_y 0
		.amdhsa_system_sgpr_workgroup_id_z 0
		.amdhsa_system_sgpr_workgroup_info 0
		.amdhsa_system_vgpr_workitem_id 0
		.amdhsa_next_free_vgpr 256
		.amdhsa_next_free_sgpr 102
		.amdhsa_accum_offset 256
		.amdhsa_reserve_vcc 1
		.amdhsa_float_round_mode_32 0
		.amdhsa_float_round_mode_16_64 0
		.amdhsa_float_denorm_mode_32 3
		.amdhsa_float_denorm_mode_16_64 3
		.amdhsa_dx10_clamp 1
		.amdhsa_ieee_mode 1
		.amdhsa_fp16_overflow 0
		.amdhsa_tg_split 0
		.amdhsa_exception_fp_ieee_invalid_op 0
		.amdhsa_exception_fp_denorm_src 0
		.amdhsa_exception_fp_ieee_div_zero 0
		.amdhsa_exception_fp_ieee_overflow 0
		.amdhsa_exception_fp_ieee_underflow 0
		.amdhsa_exception_fp_ieee_inexact 0
		.amdhsa_exception_int_div_zero 0
	.end_amdhsa_kernel

amdhsa.kernels:
  - .agpr_count:     0
    .args:
      - .offset:         0
        .size:           104
        .value_kind:     by_value
      - .offset:         104
        .size:           4
        .value_kind:     hidden_block_count_x
      - .offset:         108
        .size:           4
        .value_kind:     hidden_block_count_y
      - .offset:         112
        .size:           4
        .value_kind:     hidden_block_count_z
      - .offset:         116
        .size:           2
        .value_kind:     hidden_group_size_x
      - .offset:         118
        .size:           2
        .value_kind:     hidden_group_size_y
      - .offset:         120
        .size:           2
        .value_kind:     hidden_group_size_z
      - .offset:         122
        .size:           2
        .value_kind:     hidden_remainder_x
      - .offset:         124
        .size:           2
        .value_kind:     hidden_remainder_y
      - .offset:         126
        .size:           2
        .value_kind:     hidden_remainder_z
      - .offset:         144
        .size:           8
        .value_kind:     hidden_global_offset_x
      - .offset:         152
        .size:           8
        .value_kind:     hidden_global_offset_y
      - .offset:         160
        .size:           8
        .value_kind:     hidden_global_offset_z
      - .offset:         168
        .size:           2
        .value_kind:     hidden_grid_dims
      - .offset:         224
        .size:           4
        .value_kind:     hidden_dynamic_lds_size
    .group_segment_fixed_size: 0
    .kernarg_segment_align: 8
    .kernarg_segment_size: 360
    .language:       OpenCL C
    .language_version:
      - 2
      - 0
    .max_flat_workgroup_size: 512
    .name:           _Z6mk_fwd4Args
    .private_segment_fixed_size: 0
    .sgpr_count:     108
    .sgpr_spill_count: 283
    .symbol:         _Z6mk_fwd4Args.kd
    .uniform_work_group_size: 1
    .uses_dynamic_stack: false
    .vgpr_count:     256
    .vgpr_spill_count: 0
    .wavefront_size: 64
